# hand-written norm filler units in P2 and P4 (adaLN variant): all row loads in flight, row-invariant g/shift/scale hoisted
# speedup vs baseline: 1.0633x; 1.0031x over previous
; DI unsigned pk2(float lo, float hi) { unsigned r; asm volatile("v_cvt_pk_bf16_f32 %0, %1, %2" : "=v"(r) : "v"(lo), "v"(hi)); return r; }
; DI float shx(float v, int m, int lane) { return __int_as_float(__builtin_amdgcn_ds_bpermute((lane ^ m) << 2, __float_as_int(v))); }
; DI void norm_rows(const Params& p, int layer, int row0, int nrows, int wstart, int wstride, int tid) {
;     ...
;   for (int rowa = row0 + wstart + wid; rowa < row0 + nrows; rowa += 2 * wstride) {
;     const int rowb = (rowa + wstride < row0 + nrows) ? rowa + wstride : rowa;
;     float4 va[4], vb[4]; float sa = 0.f, sb = 0.f;
; #pragma unroll
;     for (int i = 0; i < 4; ++i) { va[i] = *(const float4*)(xin + (size_t)rowa * DM + i * 256 + lane * 4); vb[i] = *(const float4*)(xin + (size_t)rowb * DM + i * 256 + lane * 4); }
; #pragma unroll
;     for (int i = 0; i < 4; ++i) { sa += va[i].x * va[i].x + va[i].y * va[i].y + va[i].z * va[i].z + va[i].w * va[i].w; sb += vb[i].x * vb[i].x + vb[i].y * vb[i].y + vb[i].z * vb[i].z + vb[i].w * vb[i].w; }
; #pragma unroll
;     for (int o = 32; o >= 1; o >>= 1) { sa += shx(sa, o, lane); sb += shx(sb, o, lane); }
; #pragma unroll
;     for (int rr = 0; rr < 2; ++rr) {
;       const int row = rr ? rowb : rowa; const float rinv = rsqrtf((rr ? sb : sa) * (1.0f / 1024.0f) + EPS);
;       if (layer < NLAYER) {
;         const int b = row >> 13; const float* md = modb + (size_t)(layer * 4 + b) * 3072; const float* g = p.norm_g + layer * 1024;
; #pragma unroll
;         for (int i = 0; i < 4; ++i) {
;           const float4 x4 = rr ? vb[i] : va[i];
;           const int e = i * 256 + lane * 4;
;           const float4 g4 = *(const float4*)(g + e), sh = *(const float4*)(md + e), sc = *(const float4*)(md + 1024 + e);
;           uint2 w;
;           w.x = pk2(x4.x * rinv * g4.x * (1.f + sc.x) + sh.x, x4.y * rinv * g4.y * (1.f + sc.y) + sh.y);
;           w.y = pk2(x4.z * rinv * g4.z * (1.f + sc.z) + sh.z, x4.w * rinv * g4.w * (1.f + sc.w) + sh.w);
;           *(uint2*)(h + wimg_off(row, e, DM)) = w;
;         }
.LBB0_353:
	s_andn2_b64 vcc, exec, s[4:5]
	s_cbranch_vccnz .LBB0_235
	s_lshl_b32 s0, s58, 6
	s_addk_i32 s0, 0x3c00
	v_readlane_b32 s4, v254, 20
	v_readlane_b32 s5, v254, 21
	v_readlane_b32 s6, v254, 33
	v_readlane_b32 s7, v254, 34
	v_readlane_b32 s8, v252, 22
	v_readlane_b32 s9, v252, 23
	v_readlane_b32 s21, v254, 32
	v_readlane_b32 s18, v252, 48
	v_readlane_b32 s19, v252, 49
	s_lshl_b32 s1, s0, 12
	s_add_u32 s4, s4, s1
	s_addc_u32 s5, s5, 0
	s_add_u32 s6, s6, 0
	s_addc_u32 s7, s7, 0
	s_lshr_b32 s1, s0, 13
	s_add_i32 s1, s1, s21
	s_mul_i32 s1, s1, 0x3000
	s_add_u32 s8, s8, s1
	s_addc_u32 s9, s9, 0
	s_add_u32 s10, s8, 0x1000
	s_addc_u32 s11, s9, 0
	s_lshr_b32 s1, s0, 7
	s_lshl_b32 s1, s1, 18
	s_bfe_u32 s2, s0, 0x10006
	s_lshl_b32 s2, s2, 12
	s_add_u32 s1, s1, s2
	s_add_u32 s18, s18, s1
	s_addc_u32 s19, s19, 0
	v_and_b32_e32 v245, 63, v163
	v_lshrrev_b32_e32 v246, 6, v163
	v_lshlrev_b32_e32 v247, 2, v245
	v_xor_b32_e32 v236, 0x80, v247
	v_xor_b32_e32 v237, 0x40, v247
	v_xor_b32_e32 v238, 0x20, v247
	v_xor_b32_e32 v239, 0x10, v247
	v_xor_b32_e32 v240, 0x8, v247
	v_xor_b32_e32 v241, 0x4, v247
	v_lshlrev_b32_e32 v245, 4, v245
	v_lshl_add_u32 v242, v246, 12, v245
	v_and_b32_e32 v248, 63, v163
	v_lshrrev_b32_e32 v249, 3, v248
	v_and_b32_e32 v248, 7, v248
	v_lshlrev_b32_e32 v248, 3, v248
	v_lshlrev_b32_e32 v249, 13, v249
	v_lshl_add_u32 v249, v246, 6, v249
	v_add_u32_e32 v243, v249, v248
	v_xor_b32_e32 v248, 32, v248
	v_add_u32_e32 v244, v249, v248
	v_add_u32_e32 v244, 0x200, v244
	global_load_dwordx4 v[128:131], v245, s[6:7] offset:0
	global_load_dwordx4 v[132:135], v245, s[6:7] offset:1024
	global_load_dwordx4 v[136:139], v245, s[6:7] offset:2048
	global_load_dwordx4 v[140:143], v245, s[6:7] offset:3072
	global_load_dwordx4 v[144:147], v245, s[8:9] offset:0
	global_load_dwordx4 v[148:151], v245, s[8:9] offset:1024
	global_load_dwordx4 v[152:155], v245, s[8:9] offset:2048
	global_load_dwordx4 v[156:159], v245, s[8:9] offset:3072
	global_load_dwordx4 v[204:207], v245, s[10:11] offset:0
	global_load_dwordx4 v[208:211], v245, s[10:11] offset:1024
	global_load_dwordx4 v[212:215], v245, s[10:11] offset:2048
	global_load_dwordx4 v[216:219], v245, s[10:11] offset:3072
	global_load_dwordx4 v[0:3], v242, s[4:5] offset:0
	global_load_dwordx4 v[4:7], v242, s[4:5] offset:1024
	global_load_dwordx4 v[8:11], v242, s[4:5] offset:2048
	global_load_dwordx4 v[12:15], v242, s[4:5] offset:3072
	s_add_u32 s4, s4, 0x8000
	s_addc_u32 s5, s5, 0
	global_load_dwordx4 v[16:19], v242, s[4:5] offset:0
	global_load_dwordx4 v[20:23], v242, s[4:5] offset:1024
	global_load_dwordx4 v[24:27], v242, s[4:5] offset:2048
	global_load_dwordx4 v[28:31], v242, s[4:5] offset:3072
	s_add_u32 s4, s4, 0x8000
	s_addc_u32 s5, s5, 0
	global_load_dwordx4 v[32:35], v242, s[4:5] offset:0
	global_load_dwordx4 v[36:39], v242, s[4:5] offset:1024
	global_load_dwordx4 v[40:43], v242, s[4:5] offset:2048
	global_load_dwordx4 v[44:47], v242, s[4:5] offset:3072
	s_add_u32 s4, s4, 0x8000
	s_addc_u32 s5, s5, 0
	global_load_dwordx4 v[48:51], v242, s[4:5] offset:0
	global_load_dwordx4 v[52:55], v242, s[4:5] offset:1024
	global_load_dwordx4 v[56:59], v242, s[4:5] offset:2048
	global_load_dwordx4 v[60:63], v242, s[4:5] offset:3072
	s_add_u32 s4, s4, 0x8000
	s_addc_u32 s5, s5, 0
	global_load_dwordx4 v[64:67], v242, s[4:5] offset:0
	global_load_dwordx4 v[68:71], v242, s[4:5] offset:1024
	global_load_dwordx4 v[72:75], v242, s[4:5] offset:2048
	global_load_dwordx4 v[76:79], v242, s[4:5] offset:3072
	s_add_u32 s4, s4, 0x8000
	s_addc_u32 s5, s5, 0
	global_load_dwordx4 v[80:83], v242, s[4:5] offset:0
	global_load_dwordx4 v[84:87], v242, s[4:5] offset:1024
	global_load_dwordx4 v[88:91], v242, s[4:5] offset:2048
	global_load_dwordx4 v[92:95], v242, s[4:5] offset:3072
	s_add_u32 s4, s4, 0x8000
	s_addc_u32 s5, s5, 0
	global_load_dwordx4 v[96:99], v242, s[4:5] offset:0
	global_load_dwordx4 v[100:103], v242, s[4:5] offset:1024
	global_load_dwordx4 v[104:107], v242, s[4:5] offset:2048
	global_load_dwordx4 v[108:111], v242, s[4:5] offset:3072
	s_add_u32 s4, s4, 0x8000
	s_addc_u32 s5, s5, 0
	global_load_dwordx4 v[112:115], v242, s[4:5] offset:0
	global_load_dwordx4 v[116:119], v242, s[4:5] offset:1024
	global_load_dwordx4 v[120:123], v242, s[4:5] offset:2048
	global_load_dwordx4 v[124:127], v242, s[4:5] offset:3072
	s_add_u32 s20, s18, 0x10000
	s_addc_u32 s21, s19, 0
	s_add_u32 s22, s18, 0x20000
	s_addc_u32 s23, s19, 0
	s_add_u32 s24, s18, 0x30000
	s_addc_u32 s25, s19, 0
	s_mov_b32 s26, 0x3a800000
	s_waitcnt vmcnt(24)
	v_add_f32_e32 v204, 1.0, v204
	v_add_f32_e32 v205, 1.0, v205
	v_add_f32_e32 v206, 1.0, v206
	v_add_f32_e32 v207, 1.0, v207
	v_add_f32_e32 v208, 1.0, v208
	v_add_f32_e32 v209, 1.0, v209
	v_add_f32_e32 v210, 1.0, v210
	v_add_f32_e32 v211, 1.0, v211
	v_add_f32_e32 v212, 1.0, v212
	v_add_f32_e32 v213, 1.0, v213
	v_add_f32_e32 v214, 1.0, v214
	v_add_f32_e32 v215, 1.0, v215
	v_add_f32_e32 v216, 1.0, v216
	v_add_f32_e32 v217, 1.0, v217
	v_add_f32_e32 v218, 1.0, v218
	v_add_f32_e32 v219, 1.0, v219
	v_mul_f32_e32 v220, v1, v1
	v_mul_f32_e32 v224, v17, v17
	v_fmac_f32_e32 v220, v0, v0
	v_fmac_f32_e32 v224, v16, v16
	v_fmac_f32_e32 v220, v2, v2
	v_fmac_f32_e32 v224, v18, v18
	v_fmac_f32_e32 v220, v3, v3
	v_fmac_f32_e32 v224, v19, v19
	v_mul_f32_e32 v221, v5, v5
	v_mul_f32_e32 v225, v21, v21
	v_fmac_f32_e32 v221, v4, v4
	v_fmac_f32_e32 v225, v20, v20
	v_fmac_f32_e32 v221, v6, v6
	v_fmac_f32_e32 v225, v22, v22
	v_fmac_f32_e32 v221, v7, v7
	v_fmac_f32_e32 v225, v23, v23
	v_mul_f32_e32 v222, v9, v9
	v_mul_f32_e32 v226, v25, v25
	v_fmac_f32_e32 v222, v8, v8
	v_fmac_f32_e32 v226, v24, v24
	v_fmac_f32_e32 v222, v10, v10
	v_fmac_f32_e32 v226, v26, v26
	v_fmac_f32_e32 v222, v11, v11
	v_fmac_f32_e32 v226, v27, v27
	v_mul_f32_e32 v223, v13, v13
	v_mul_f32_e32 v227, v29, v29
	v_fmac_f32_e32 v223, v12, v12
	v_fmac_f32_e32 v227, v28, v28
	v_fmac_f32_e32 v223, v14, v14
	v_fmac_f32_e32 v227, v30, v30
	v_fmac_f32_e32 v223, v15, v15
	v_fmac_f32_e32 v227, v31, v31
	v_add_f32_e32 v228, v220, v221
	v_add_f32_e32 v229, v224, v225
	v_add_f32_e32 v228, v228, v222
	v_add_f32_e32 v229, v229, v226
	v_add_f32_e32 v228, v228, v223
	v_add_f32_e32 v229, v229, v227
	ds_bpermute_b32 v230, v236, v228
	ds_bpermute_b32 v231, v236, v229
	s_waitcnt lgkmcnt(0)
; DI unsigned pk2(float lo, float hi) { unsigned r; asm volatile("v_cvt_pk_bf16_f32 %0, %1, %2" : "=v"(r) : "v"(lo), "v"(hi)); return r; }
; DI float shx(float v, int m, int lane) { return __int_as_float(__builtin_amdgcn_ds_bpermute((lane ^ m) << 2, __float_as_int(v))); }
; DI void norm_rows(const Params& p, int layer, int row0, int nrows, int wstart, int wstride, int tid) {
;     ...
;     for (int o = 32; o >= 1; o >>= 1) { sa += shx(sa, o, lane); sb += shx(sb, o, lane); }
; #pragma unroll
;     for (int rr = 0; rr < 2; ++rr) {
;       const int row = rr ? rowb : rowa; const float rinv = rsqrtf((rr ? sb : sa) * (1.0f / 1024.0f) + EPS);
;       if (layer < NLAYER) {
;         const int b = row >> 13; const float* md = modb + (size_t)(layer * 4 + b) * 3072; const float* g = p.norm_g + layer * 1024;
; #pragma unroll
;         for (int i = 0; i < 4; ++i) {
;           const float4 x4 = rr ? vb[i] : va[i];
;           const int e = i * 256 + lane * 4;
;           const float4 g4 = *(const float4*)(g + e), sh = *(const float4*)(md + e), sc = *(const float4*)(md + 1024 + e);
;           uint2 w;
;           w.x = pk2(x4.x * rinv * g4.x * (1.f + sc.x) + sh.x, x4.y * rinv * g4.y * (1.f + sc.y) + sh.y);
;           w.y = pk2(x4.z * rinv * g4.z * (1.f + sc.z) + sh.z, x4.w * rinv * g4.w * (1.f + sc.w) + sh.w);
;           *(uint2*)(h + wimg_off(row, e, DM)) = w;
;         }
	v_add_f32_e32 v228, v228, v230
	v_add_f32_e32 v229, v229, v231
	ds_bpermute_b32 v230, v237, v228
	ds_bpermute_b32 v231, v237, v229
	s_waitcnt lgkmcnt(0)
	v_add_f32_e32 v228, v228, v230
	v_add_f32_e32 v229, v229, v231
	ds_bpermute_b32 v230, v238, v228
	ds_bpermute_b32 v231, v238, v229
	s_waitcnt lgkmcnt(0)
	v_add_f32_e32 v228, v228, v230
	v_add_f32_e32 v229, v229, v231
	ds_bpermute_b32 v230, v239, v228
	ds_bpermute_b32 v231, v239, v229
	s_waitcnt lgkmcnt(0)
	v_add_f32_e32 v228, v228, v230
	v_add_f32_e32 v229, v229, v231
	ds_bpermute_b32 v230, v240, v228
	ds_bpermute_b32 v231, v240, v229
	s_waitcnt lgkmcnt(0)
	v_add_f32_e32 v228, v228, v230
	v_add_f32_e32 v229, v229, v231
	ds_bpermute_b32 v230, v241, v228
	ds_bpermute_b32 v231, v241, v229
	s_waitcnt lgkmcnt(0)
	v_add_f32_e32 v228, v228, v230
	v_add_f32_e32 v229, v229, v231
	v_fma_f32 v228, v228, s26, v162
	v_fma_f32 v229, v229, s26, v162
	v_rsq_f32_e32 v232, v228
	v_rsq_f32_e32 v233, v229
	s_nop 0
	v_mul_f32_e32 v0, v0, v232
	v_mul_f32_e32 v1, v1, v232
	v_mul_f32_e32 v2, v2, v232
	v_mul_f32_e32 v3, v3, v232
	v_mul_f32_e32 v0, v128, v0
	v_mul_f32_e32 v1, v129, v1
	v_mul_f32_e32 v2, v130, v2
	v_mul_f32_e32 v3, v131, v3
	v_fma_f32 v0, v0, v204, v144
	v_fma_f32 v1, v1, v205, v145
	v_fma_f32 v2, v2, v206, v146
	v_fma_f32 v3, v3, v207, v147
	v_cvt_pk_bf16_f32 v234, v0, v1
	v_cvt_pk_bf16_f32 v235, v2, v3
	s_nop 0
	global_store_dwordx2 v243, v[234:235], s[18:19] offset:0
	v_mul_f32_e32 v4, v4, v232
	v_mul_f32_e32 v5, v5, v232
	v_mul_f32_e32 v6, v6, v232
	v_mul_f32_e32 v7, v7, v232
	v_mul_f32_e32 v4, v132, v4
	v_mul_f32_e32 v5, v133, v5
	v_mul_f32_e32 v6, v134, v6
	v_mul_f32_e32 v7, v135, v7
	v_fma_f32 v4, v4, v208, v148
	v_fma_f32 v5, v5, v209, v149
	v_fma_f32 v6, v6, v210, v150
	v_fma_f32 v7, v7, v211, v151
	v_cvt_pk_bf16_f32 v234, v4, v5
	v_cvt_pk_bf16_f32 v235, v6, v7
	s_nop 0
	global_store_dwordx2 v243, v[234:235], s[20:21] offset:0
	v_mul_f32_e32 v8, v8, v232
	v_mul_f32_e32 v9, v9, v232
	v_mul_f32_e32 v10, v10, v232
	v_mul_f32_e32 v11, v11, v232
	v_mul_f32_e32 v8, v136, v8
	v_mul_f32_e32 v9, v137, v9
	v_mul_f32_e32 v10, v138, v10
	v_mul_f32_e32 v11, v139, v11
	v_fma_f32 v8, v8, v212, v152
	v_fma_f32 v9, v9, v213, v153
	v_fma_f32 v10, v10, v214, v154
	v_fma_f32 v11, v11, v215, v155
	v_cvt_pk_bf16_f32 v234, v8, v9
	v_cvt_pk_bf16_f32 v235, v10, v11
	s_nop 0
	global_store_dwordx2 v243, v[234:235], s[22:23] offset:0
	v_mul_f32_e32 v12, v12, v232
	v_mul_f32_e32 v13, v13, v232
	v_mul_f32_e32 v14, v14, v232
	v_mul_f32_e32 v15, v15, v232
	v_mul_f32_e32 v12, v140, v12
	v_mul_f32_e32 v13, v141, v13
	v_mul_f32_e32 v14, v142, v14
	v_mul_f32_e32 v15, v143, v15
	v_fma_f32 v12, v12, v216, v156
	v_fma_f32 v13, v13, v217, v157
	v_fma_f32 v14, v14, v218, v158
	v_fma_f32 v15, v15, v219, v159
	v_cvt_pk_bf16_f32 v234, v12, v13
	v_cvt_pk_bf16_f32 v235, v14, v15
	s_nop 0
	global_store_dwordx2 v243, v[234:235], s[24:25] offset:0
	v_mul_f32_e32 v16, v16, v233
	v_mul_f32_e32 v17, v17, v233
	v_mul_f32_e32 v18, v18, v233
	v_mul_f32_e32 v19, v19, v233
	v_mul_f32_e32 v16, v128, v16
	v_mul_f32_e32 v17, v129, v17
	v_mul_f32_e32 v18, v130, v18
	v_mul_f32_e32 v19, v131, v19
	v_fma_f32 v16, v16, v204, v144
	v_fma_f32 v17, v17, v205, v145
	v_fma_f32 v18, v18, v206, v146
	v_fma_f32 v19, v19, v207, v147
	v_cvt_pk_bf16_f32 v234, v16, v17
	v_cvt_pk_bf16_f32 v235, v18, v19
	s_nop 0
	global_store_dwordx2 v244, v[234:235], s[18:19] offset:0
	v_mul_f32_e32 v20, v20, v233
	v_mul_f32_e32 v21, v21, v233
	v_mul_f32_e32 v22, v22, v233
	v_mul_f32_e32 v23, v23, v233
	v_mul_f32_e32 v20, v132, v20
	v_mul_f32_e32 v21, v133, v21
	v_mul_f32_e32 v22, v134, v22
	v_mul_f32_e32 v23, v135, v23
	v_fma_f32 v20, v20, v208, v148
	v_fma_f32 v21, v21, v209, v149
	v_fma_f32 v22, v22, v210, v150
	v_fma_f32 v23, v23, v211, v151
	v_cvt_pk_bf16_f32 v234, v20, v21
	v_cvt_pk_bf16_f32 v235, v22, v23
	s_nop 0
	global_store_dwordx2 v244, v[234:235], s[20:21] offset:0
	v_mul_f32_e32 v24, v24, v233
	v_mul_f32_e32 v25, v25, v233
	v_mul_f32_e32 v26, v26, v233
	v_mul_f32_e32 v27, v27, v233
	v_mul_f32_e32 v24, v136, v24
	v_mul_f32_e32 v25, v137, v25
	v_mul_f32_e32 v26, v138, v26
	v_mul_f32_e32 v27, v139, v27
	v_fma_f32 v24, v24, v212, v152
	v_fma_f32 v25, v25, v213, v153
	v_fma_f32 v26, v26, v214, v154
	v_fma_f32 v27, v27, v215, v155
	v_cvt_pk_bf16_f32 v234, v24, v25
	v_cvt_pk_bf16_f32 v235, v26, v27
	s_nop 0
	global_store_dwordx2 v244, v[234:235], s[22:23] offset:0
	v_mul_f32_e32 v28, v28, v233
	v_mul_f32_e32 v29, v29, v233
	v_mul_f32_e32 v30, v30, v233
	v_mul_f32_e32 v31, v31, v233
	v_mul_f32_e32 v28, v140, v28
	v_mul_f32_e32 v29, v141, v29
	v_mul_f32_e32 v30, v142, v30
	v_mul_f32_e32 v31, v143, v31
	v_fma_f32 v28, v28, v216, v156
	v_fma_f32 v29, v29, v217, v157
	v_fma_f32 v30, v30, v218, v158
	v_fma_f32 v31, v31, v219, v159
	v_cvt_pk_bf16_f32 v234, v28, v29
	v_cvt_pk_bf16_f32 v235, v30, v31
	s_nop 0
	global_store_dwordx2 v244, v[234:235], s[24:25] offset:0
	s_waitcnt vmcnt(24)
	v_mul_f32_e32 v220, v33, v33
	v_mul_f32_e32 v224, v49, v49
	v_fmac_f32_e32 v220, v32, v32
	v_fmac_f32_e32 v224, v48, v48
	v_fmac_f32_e32 v220, v34, v34
	v_fmac_f32_e32 v224, v50, v50
	v_fmac_f32_e32 v220, v35, v35
	v_fmac_f32_e32 v224, v51, v51
	v_mul_f32_e32 v221, v37, v37
	v_mul_f32_e32 v225, v53, v53
	v_fmac_f32_e32 v221, v36, v36
	v_fmac_f32_e32 v225, v52, v52
	v_fmac_f32_e32 v221, v38, v38
	v_fmac_f32_e32 v225, v54, v54
	v_fmac_f32_e32 v221, v39, v39
	v_fmac_f32_e32 v225, v55, v55
	v_mul_f32_e32 v222, v41, v41
	v_mul_f32_e32 v226, v57, v57
	v_fmac_f32_e32 v222, v40, v40
	v_fmac_f32_e32 v226, v56, v56
	v_fmac_f32_e32 v222, v42, v42
	v_fmac_f32_e32 v226, v58, v58
	v_fmac_f32_e32 v222, v43, v43
	v_fmac_f32_e32 v226, v59, v59
	v_mul_f32_e32 v223, v45, v45
	v_mul_f32_e32 v227, v61, v61
	v_fmac_f32_e32 v223, v44, v44
	v_fmac_f32_e32 v227, v60, v60
	v_fmac_f32_e32 v223, v46, v46
	v_fmac_f32_e32 v227, v62, v62
	v_fmac_f32_e32 v223, v47, v47
	v_fmac_f32_e32 v227, v63, v63
	v_add_f32_e32 v228, v220, v221
	v_add_f32_e32 v229, v224, v225
	v_add_f32_e32 v228, v228, v222
	v_add_f32_e32 v229, v229, v226
	v_add_f32_e32 v228, v228, v223
	v_add_f32_e32 v229, v229, v227
	ds_bpermute_b32 v230, v236, v228
	ds_bpermute_b32 v231, v236, v229
	s_waitcnt lgkmcnt(0)
; DI unsigned pk2(float lo, float hi) { unsigned r; asm volatile("v_cvt_pk_bf16_f32 %0, %1, %2" : "=v"(r) : "v"(lo), "v"(hi)); return r; }
; DI float shx(float v, int m, int lane) { return __int_as_float(__builtin_amdgcn_ds_bpermute((lane ^ m) << 2, __float_as_int(v))); }
; DI void norm_rows(const Params& p, int layer, int row0, int nrows, int wstart, int wstride, int tid) {
;     ...
;     for (int o = 32; o >= 1; o >>= 1) { sa += shx(sa, o, lane); sb += shx(sb, o, lane); }
; #pragma unroll
;     for (int rr = 0; rr < 2; ++rr) {
;       const int row = rr ? rowb : rowa; const float rinv = rsqrtf((rr ? sb : sa) * (1.0f / 1024.0f) + EPS);
;       if (layer < NLAYER) {
;         const int b = row >> 13; const float* md = modb + (size_t)(layer * 4 + b) * 3072; const float* g = p.norm_g + layer * 1024;
; #pragma unroll
;         for (int i = 0; i < 4; ++i) {
;           const float4 x4 = rr ? vb[i] : va[i];
;           const int e = i * 256 + lane * 4;
;           const float4 g4 = *(const float4*)(g + e), sh = *(const float4*)(md + e), sc = *(const float4*)(md + 1024 + e);
;           uint2 w;
;           w.x = pk2(x4.x * rinv * g4.x * (1.f + sc.x) + sh.x, x4.y * rinv * g4.y * (1.f + sc.y) + sh.y);
;           w.y = pk2(x4.z * rinv * g4.z * (1.f + sc.z) + sh.z, x4.w * rinv * g4.w * (1.f + sc.w) + sh.w);
;           *(uint2*)(h + wimg_off(row, e, DM)) = w;
;         }
	v_add_f32_e32 v228, v228, v230
	v_add_f32_e32 v229, v229, v231
	ds_bpermute_b32 v230, v237, v228
	ds_bpermute_b32 v231, v237, v229
	s_waitcnt lgkmcnt(0)
	v_add_f32_e32 v228, v228, v230
	v_add_f32_e32 v229, v229, v231
	ds_bpermute_b32 v230, v238, v228
	ds_bpermute_b32 v231, v238, v229
	s_waitcnt lgkmcnt(0)
	v_add_f32_e32 v228, v228, v230
	v_add_f32_e32 v229, v229, v231
	ds_bpermute_b32 v230, v239, v228
	ds_bpermute_b32 v231, v239, v229
	s_waitcnt lgkmcnt(0)
	v_add_f32_e32 v228, v228, v230
	v_add_f32_e32 v229, v229, v231
	ds_bpermute_b32 v230, v240, v228
	ds_bpermute_b32 v231, v240, v229
	s_waitcnt lgkmcnt(0)
	v_add_f32_e32 v228, v228, v230
	v_add_f32_e32 v229, v229, v231
	ds_bpermute_b32 v230, v241, v228
	ds_bpermute_b32 v231, v241, v229
	s_waitcnt lgkmcnt(0)
	v_add_f32_e32 v228, v228, v230
	v_add_f32_e32 v229, v229, v231
	v_fma_f32 v228, v228, s26, v162
	v_fma_f32 v229, v229, s26, v162
	v_rsq_f32_e32 v232, v228
	v_rsq_f32_e32 v233, v229
	s_nop 0
	v_mul_f32_e32 v32, v32, v232
	v_mul_f32_e32 v33, v33, v232
	v_mul_f32_e32 v34, v34, v232
	v_mul_f32_e32 v35, v35, v232
	v_mul_f32_e32 v32, v128, v32
	v_mul_f32_e32 v33, v129, v33
	v_mul_f32_e32 v34, v130, v34
	v_mul_f32_e32 v35, v131, v35
	v_fma_f32 v32, v32, v204, v144
	v_fma_f32 v33, v33, v205, v145
	v_fma_f32 v34, v34, v206, v146
	v_fma_f32 v35, v35, v207, v147
	v_cvt_pk_bf16_f32 v234, v32, v33
	v_cvt_pk_bf16_f32 v235, v34, v35
	s_nop 0
	global_store_dwordx2 v243, v[234:235], s[18:19] offset:1024
	v_mul_f32_e32 v36, v36, v232
	v_mul_f32_e32 v37, v37, v232
	v_mul_f32_e32 v38, v38, v232
	v_mul_f32_e32 v39, v39, v232
	v_mul_f32_e32 v36, v132, v36
	v_mul_f32_e32 v37, v133, v37
	v_mul_f32_e32 v38, v134, v38
	v_mul_f32_e32 v39, v135, v39
	v_fma_f32 v36, v36, v208, v148
	v_fma_f32 v37, v37, v209, v149
	v_fma_f32 v38, v38, v210, v150
	v_fma_f32 v39, v39, v211, v151
	v_cvt_pk_bf16_f32 v234, v36, v37
	v_cvt_pk_bf16_f32 v235, v38, v39
	s_nop 0
	global_store_dwordx2 v243, v[234:235], s[20:21] offset:1024
	v_mul_f32_e32 v40, v40, v232
	v_mul_f32_e32 v41, v41, v232
	v_mul_f32_e32 v42, v42, v232
	v_mul_f32_e32 v43, v43, v232
	v_mul_f32_e32 v40, v136, v40
	v_mul_f32_e32 v41, v137, v41
	v_mul_f32_e32 v42, v138, v42
	v_mul_f32_e32 v43, v139, v43
	v_fma_f32 v40, v40, v212, v152
	v_fma_f32 v41, v41, v213, v153
	v_fma_f32 v42, v42, v214, v154
	v_fma_f32 v43, v43, v215, v155
	v_cvt_pk_bf16_f32 v234, v40, v41
	v_cvt_pk_bf16_f32 v235, v42, v43
	s_nop 0
	global_store_dwordx2 v243, v[234:235], s[22:23] offset:1024
	v_mul_f32_e32 v44, v44, v232
	v_mul_f32_e32 v45, v45, v232
	v_mul_f32_e32 v46, v46, v232
	v_mul_f32_e32 v47, v47, v232
	v_mul_f32_e32 v44, v140, v44
	v_mul_f32_e32 v45, v141, v45
	v_mul_f32_e32 v46, v142, v46
	v_mul_f32_e32 v47, v143, v47
	v_fma_f32 v44, v44, v216, v156
	v_fma_f32 v45, v45, v217, v157
	v_fma_f32 v46, v46, v218, v158
	v_fma_f32 v47, v47, v219, v159
	v_cvt_pk_bf16_f32 v234, v44, v45
	v_cvt_pk_bf16_f32 v235, v46, v47
	s_nop 0
	global_store_dwordx2 v243, v[234:235], s[24:25] offset:1024
	v_mul_f32_e32 v48, v48, v233
	v_mul_f32_e32 v49, v49, v233
	v_mul_f32_e32 v50, v50, v233
	v_mul_f32_e32 v51, v51, v233
	v_mul_f32_e32 v48, v128, v48
	v_mul_f32_e32 v49, v129, v49
	v_mul_f32_e32 v50, v130, v50
	v_mul_f32_e32 v51, v131, v51
	v_fma_f32 v48, v48, v204, v144
	v_fma_f32 v49, v49, v205, v145
	v_fma_f32 v50, v50, v206, v146
	v_fma_f32 v51, v51, v207, v147
	v_cvt_pk_bf16_f32 v234, v48, v49
	v_cvt_pk_bf16_f32 v235, v50, v51
	s_nop 0
	global_store_dwordx2 v244, v[234:235], s[18:19] offset:1024
	v_mul_f32_e32 v52, v52, v233
	v_mul_f32_e32 v53, v53, v233
	v_mul_f32_e32 v54, v54, v233
	v_mul_f32_e32 v55, v55, v233
	v_mul_f32_e32 v52, v132, v52
	v_mul_f32_e32 v53, v133, v53
	v_mul_f32_e32 v54, v134, v54
	v_mul_f32_e32 v55, v135, v55
	v_fma_f32 v52, v52, v208, v148
	v_fma_f32 v53, v53, v209, v149
	v_fma_f32 v54, v54, v210, v150
	v_fma_f32 v55, v55, v211, v151
	v_cvt_pk_bf16_f32 v234, v52, v53
	v_cvt_pk_bf16_f32 v235, v54, v55
	s_nop 0
	global_store_dwordx2 v244, v[234:235], s[20:21] offset:1024
	v_mul_f32_e32 v56, v56, v233
	v_mul_f32_e32 v57, v57, v233
	v_mul_f32_e32 v58, v58, v233
	v_mul_f32_e32 v59, v59, v233
	v_mul_f32_e32 v56, v136, v56
	v_mul_f32_e32 v57, v137, v57
	v_mul_f32_e32 v58, v138, v58
	v_mul_f32_e32 v59, v139, v59
	v_fma_f32 v56, v56, v212, v152
	v_fma_f32 v57, v57, v213, v153
	v_fma_f32 v58, v58, v214, v154
	v_fma_f32 v59, v59, v215, v155
	v_cvt_pk_bf16_f32 v234, v56, v57
	v_cvt_pk_bf16_f32 v235, v58, v59
	s_nop 0
	global_store_dwordx2 v244, v[234:235], s[22:23] offset:1024
	v_mul_f32_e32 v60, v60, v233
	v_mul_f32_e32 v61, v61, v233
	v_mul_f32_e32 v62, v62, v233
	v_mul_f32_e32 v63, v63, v233
	v_mul_f32_e32 v60, v140, v60
	v_mul_f32_e32 v61, v141, v61
	v_mul_f32_e32 v62, v142, v62
	v_mul_f32_e32 v63, v143, v63
	v_fma_f32 v60, v60, v216, v156
	v_fma_f32 v61, v61, v217, v157
	v_fma_f32 v62, v62, v218, v158
	v_fma_f32 v63, v63, v219, v159
	v_cvt_pk_bf16_f32 v234, v60, v61
	v_cvt_pk_bf16_f32 v235, v62, v63
	s_nop 0
	global_store_dwordx2 v244, v[234:235], s[24:25] offset:1024
	s_waitcnt vmcnt(24)
; DI unsigned pk2(float lo, float hi) { unsigned r; asm volatile("v_cvt_pk_bf16_f32 %0, %1, %2" : "=v"(r) : "v"(lo), "v"(hi)); return r; }
; DI float shx(float v, int m, int lane) { return __int_as_float(__builtin_amdgcn_ds_bpermute((lane ^ m) << 2, __float_as_int(v))); }
; DI void norm_rows(const Params& p, int layer, int row0, int nrows, int wstart, int wstride, int tid) {
;     ...
;     for (int i = 0; i < 4; ++i) { sa += va[i].x * va[i].x + va[i].y * va[i].y + va[i].z * va[i].z + va[i].w * va[i].w; sb += vb[i].x * vb[i].x + vb[i].y * vb[i].y + vb[i].z * vb[i].z + vb[i].w * vb[i].w; }
; #pragma unroll
;     for (int o = 32; o >= 1; o >>= 1) { sa += shx(sa, o, lane); sb += shx(sb, o, lane); }
; #pragma unroll
;     for (int rr = 0; rr < 2; ++rr) {
;       const int row = rr ? rowb : rowa; const float rinv = rsqrtf((rr ? sb : sa) * (1.0f / 1024.0f) + EPS);
;       if (layer < NLAYER) {
;         const int b = row >> 13; const float* md = modb + (size_t)(layer * 4 + b) * 3072; const float* g = p.norm_g + layer * 1024;
; #pragma unroll
;         for (int i = 0; i < 4; ++i) {
;           const float4 x4 = rr ? vb[i] : va[i];
;           const int e = i * 256 + lane * 4;
;           const float4 g4 = *(const float4*)(g + e), sh = *(const float4*)(md + e), sc = *(const float4*)(md + 1024 + e);
;           uint2 w;
;           w.x = pk2(x4.x * rinv * g4.x * (1.f + sc.x) + sh.x, x4.y * rinv * g4.y * (1.f + sc.y) + sh.y);
;           w.y = pk2(x4.z * rinv * g4.z * (1.f + sc.z) + sh.z, x4.w * rinv * g4.w * (1.f + sc.w) + sh.w);
;           *(uint2*)(h + wimg_off(row, e, DM)) = w;
;         }
	v_mul_f32_e32 v220, v65, v65
	v_mul_f32_e32 v224, v81, v81
	v_fmac_f32_e32 v220, v64, v64
	v_fmac_f32_e32 v224, v80, v80
	v_fmac_f32_e32 v220, v66, v66
	v_fmac_f32_e32 v224, v82, v82
	v_fmac_f32_e32 v220, v67, v67
	v_fmac_f32_e32 v224, v83, v83
	v_mul_f32_e32 v221, v69, v69
	v_mul_f32_e32 v225, v85, v85
	v_fmac_f32_e32 v221, v68, v68
	v_fmac_f32_e32 v225, v84, v84
	v_fmac_f32_e32 v221, v70, v70
	v_fmac_f32_e32 v225, v86, v86
	v_fmac_f32_e32 v221, v71, v71
	v_fmac_f32_e32 v225, v87, v87
	v_mul_f32_e32 v222, v73, v73
	v_mul_f32_e32 v226, v89, v89
	v_fmac_f32_e32 v222, v72, v72
	v_fmac_f32_e32 v226, v88, v88
	v_fmac_f32_e32 v222, v74, v74
	v_fmac_f32_e32 v226, v90, v90
	v_fmac_f32_e32 v222, v75, v75
	v_fmac_f32_e32 v226, v91, v91
	v_mul_f32_e32 v223, v77, v77
	v_mul_f32_e32 v227, v93, v93
	v_fmac_f32_e32 v223, v76, v76
	v_fmac_f32_e32 v227, v92, v92
	v_fmac_f32_e32 v223, v78, v78
	v_fmac_f32_e32 v227, v94, v94
	v_fmac_f32_e32 v223, v79, v79
	v_fmac_f32_e32 v227, v95, v95
	v_add_f32_e32 v228, v220, v221
	v_add_f32_e32 v229, v224, v225
	v_add_f32_e32 v228, v228, v222
	v_add_f32_e32 v229, v229, v226
	v_add_f32_e32 v228, v228, v223
	v_add_f32_e32 v229, v229, v227
	ds_bpermute_b32 v230, v236, v228
	ds_bpermute_b32 v231, v236, v229
	s_waitcnt lgkmcnt(0)
	v_add_f32_e32 v228, v228, v230
	v_add_f32_e32 v229, v229, v231
	ds_bpermute_b32 v230, v237, v228
	ds_bpermute_b32 v231, v237, v229
	s_waitcnt lgkmcnt(0)
	v_add_f32_e32 v228, v228, v230
	v_add_f32_e32 v229, v229, v231
	ds_bpermute_b32 v230, v238, v228
	ds_bpermute_b32 v231, v238, v229
	s_waitcnt lgkmcnt(0)
	v_add_f32_e32 v228, v228, v230
	v_add_f32_e32 v229, v229, v231
	ds_bpermute_b32 v230, v239, v228
	ds_bpermute_b32 v231, v239, v229
	s_waitcnt lgkmcnt(0)
	v_add_f32_e32 v228, v228, v230
	v_add_f32_e32 v229, v229, v231
	ds_bpermute_b32 v230, v240, v228
	ds_bpermute_b32 v231, v240, v229
	s_waitcnt lgkmcnt(0)
	v_add_f32_e32 v228, v228, v230
	v_add_f32_e32 v229, v229, v231
	ds_bpermute_b32 v230, v241, v228
	ds_bpermute_b32 v231, v241, v229
	s_waitcnt lgkmcnt(0)
	v_add_f32_e32 v228, v228, v230
	v_add_f32_e32 v229, v229, v231
	v_fma_f32 v228, v228, s26, v162
	v_fma_f32 v229, v229, s26, v162
	v_rsq_f32_e32 v232, v228
	v_rsq_f32_e32 v233, v229
	s_nop 0
	v_mul_f32_e32 v64, v64, v232
	v_mul_f32_e32 v65, v65, v232
	v_mul_f32_e32 v66, v66, v232
	v_mul_f32_e32 v67, v67, v232
	v_mul_f32_e32 v64, v128, v64
	v_mul_f32_e32 v65, v129, v65
	v_mul_f32_e32 v66, v130, v66
	v_mul_f32_e32 v67, v131, v67
	v_fma_f32 v64, v64, v204, v144
	v_fma_f32 v65, v65, v205, v145
	v_fma_f32 v66, v66, v206, v146
	v_fma_f32 v67, v67, v207, v147
	v_cvt_pk_bf16_f32 v234, v64, v65
	v_cvt_pk_bf16_f32 v235, v66, v67
	s_nop 0
	global_store_dwordx2 v243, v[234:235], s[18:19] offset:2048
	v_mul_f32_e32 v68, v68, v232
	v_mul_f32_e32 v69, v69, v232
	v_mul_f32_e32 v70, v70, v232
	v_mul_f32_e32 v71, v71, v232
	v_mul_f32_e32 v68, v132, v68
	v_mul_f32_e32 v69, v133, v69
	v_mul_f32_e32 v70, v134, v70
	v_mul_f32_e32 v71, v135, v71
	v_fma_f32 v68, v68, v208, v148
	v_fma_f32 v69, v69, v209, v149
	v_fma_f32 v70, v70, v210, v150
	v_fma_f32 v71, v71, v211, v151
	v_cvt_pk_bf16_f32 v234, v68, v69
	v_cvt_pk_bf16_f32 v235, v70, v71
	s_nop 0
	global_store_dwordx2 v243, v[234:235], s[20:21] offset:2048
	v_mul_f32_e32 v72, v72, v232
	v_mul_f32_e32 v73, v73, v232
	v_mul_f32_e32 v74, v74, v232
	v_mul_f32_e32 v75, v75, v232
	v_mul_f32_e32 v72, v136, v72
	v_mul_f32_e32 v73, v137, v73
	v_mul_f32_e32 v74, v138, v74
	v_mul_f32_e32 v75, v139, v75
	v_fma_f32 v72, v72, v212, v152
	v_fma_f32 v73, v73, v213, v153
	v_fma_f32 v74, v74, v214, v154
	v_fma_f32 v75, v75, v215, v155
	v_cvt_pk_bf16_f32 v234, v72, v73
	v_cvt_pk_bf16_f32 v235, v74, v75
	s_nop 0
	global_store_dwordx2 v243, v[234:235], s[22:23] offset:2048
	v_mul_f32_e32 v76, v76, v232
	v_mul_f32_e32 v77, v77, v232
	v_mul_f32_e32 v78, v78, v232
	v_mul_f32_e32 v79, v79, v232
	v_mul_f32_e32 v76, v140, v76
	v_mul_f32_e32 v77, v141, v77
	v_mul_f32_e32 v78, v142, v78
	v_mul_f32_e32 v79, v143, v79
	v_fma_f32 v76, v76, v216, v156
	v_fma_f32 v77, v77, v217, v157
	v_fma_f32 v78, v78, v218, v158
	v_fma_f32 v79, v79, v219, v159
	v_cvt_pk_bf16_f32 v234, v76, v77
	v_cvt_pk_bf16_f32 v235, v78, v79
	s_nop 0
	global_store_dwordx2 v243, v[234:235], s[24:25] offset:2048
	v_mul_f32_e32 v80, v80, v233
	v_mul_f32_e32 v81, v81, v233
	v_mul_f32_e32 v82, v82, v233
	v_mul_f32_e32 v83, v83, v233
	v_mul_f32_e32 v80, v128, v80
	v_mul_f32_e32 v81, v129, v81
	v_mul_f32_e32 v82, v130, v82
	v_mul_f32_e32 v83, v131, v83
	v_fma_f32 v80, v80, v204, v144
	v_fma_f32 v81, v81, v205, v145
	v_fma_f32 v82, v82, v206, v146
	v_fma_f32 v83, v83, v207, v147
	v_cvt_pk_bf16_f32 v234, v80, v81
	v_cvt_pk_bf16_f32 v235, v82, v83
	s_nop 0
	global_store_dwordx2 v244, v[234:235], s[18:19] offset:2048
	v_mul_f32_e32 v84, v84, v233
	v_mul_f32_e32 v85, v85, v233
	v_mul_f32_e32 v86, v86, v233
	v_mul_f32_e32 v87, v87, v233
	v_mul_f32_e32 v84, v132, v84
	v_mul_f32_e32 v85, v133, v85
	v_mul_f32_e32 v86, v134, v86
	v_mul_f32_e32 v87, v135, v87
	v_fma_f32 v84, v84, v208, v148
	v_fma_f32 v85, v85, v209, v149
	v_fma_f32 v86, v86, v210, v150
	v_fma_f32 v87, v87, v211, v151
	v_cvt_pk_bf16_f32 v234, v84, v85
	v_cvt_pk_bf16_f32 v235, v86, v87
	s_nop 0
	global_store_dwordx2 v244, v[234:235], s[20:21] offset:2048
	v_mul_f32_e32 v88, v88, v233
	v_mul_f32_e32 v89, v89, v233
	v_mul_f32_e32 v90, v90, v233
	v_mul_f32_e32 v91, v91, v233
	v_mul_f32_e32 v88, v136, v88
	v_mul_f32_e32 v89, v137, v89
	v_mul_f32_e32 v90, v138, v90
	v_mul_f32_e32 v91, v139, v91
	v_fma_f32 v88, v88, v212, v152
	v_fma_f32 v89, v89, v213, v153
	v_fma_f32 v90, v90, v214, v154
	v_fma_f32 v91, v91, v215, v155
	v_cvt_pk_bf16_f32 v234, v88, v89
	v_cvt_pk_bf16_f32 v235, v90, v91
	s_nop 0
	global_store_dwordx2 v244, v[234:235], s[22:23] offset:2048
	v_mul_f32_e32 v92, v92, v233
	v_mul_f32_e32 v93, v93, v233
	v_mul_f32_e32 v94, v94, v233
	v_mul_f32_e32 v95, v95, v233
	v_mul_f32_e32 v92, v140, v92
	v_mul_f32_e32 v93, v141, v93
	v_mul_f32_e32 v94, v142, v94
	v_mul_f32_e32 v95, v143, v95
	v_fma_f32 v92, v92, v216, v156
	v_fma_f32 v93, v93, v217, v157
	v_fma_f32 v94, v94, v218, v158
	v_fma_f32 v95, v95, v219, v159
	v_cvt_pk_bf16_f32 v234, v92, v93
	v_cvt_pk_bf16_f32 v235, v94, v95
	s_nop 0
	global_store_dwordx2 v244, v[234:235], s[24:25] offset:2048
	s_waitcnt vmcnt(24)
; DI unsigned pk2(float lo, float hi) { unsigned r; asm volatile("v_cvt_pk_bf16_f32 %0, %1, %2" : "=v"(r) : "v"(lo), "v"(hi)); return r; }
; DI float shx(float v, int m, int lane) { return __int_as_float(__builtin_amdgcn_ds_bpermute((lane ^ m) << 2, __float_as_int(v))); }
; DI void norm_rows(const Params& p, int layer, int row0, int nrows, int wstart, int wstride, int tid) {
;     ...
;     for (int i = 0; i < 4; ++i) { sa += va[i].x * va[i].x + va[i].y * va[i].y + va[i].z * va[i].z + va[i].w * va[i].w; sb += vb[i].x * vb[i].x + vb[i].y * vb[i].y + vb[i].z * vb[i].z + vb[i].w * vb[i].w; }
; #pragma unroll
;     for (int o = 32; o >= 1; o >>= 1) { sa += shx(sa, o, lane); sb += shx(sb, o, lane); }
; #pragma unroll
;     for (int rr = 0; rr < 2; ++rr) {
;       const int row = rr ? rowb : rowa; const float rinv = rsqrtf((rr ? sb : sa) * (1.0f / 1024.0f) + EPS);
;       if (layer < NLAYER) {
;         const int b = row >> 13; const float* md = modb + (size_t)(layer * 4 + b) * 3072; const float* g = p.norm_g + layer * 1024;
; #pragma unroll
;         for (int i = 0; i < 4; ++i) {
;           const float4 x4 = rr ? vb[i] : va[i];
;           const int e = i * 256 + lane * 4;
;           const float4 g4 = *(const float4*)(g + e), sh = *(const float4*)(md + e), sc = *(const float4*)(md + 1024 + e);
;           uint2 w;
;           w.x = pk2(x4.x * rinv * g4.x * (1.f + sc.x) + sh.x, x4.y * rinv * g4.y * (1.f + sc.y) + sh.y);
;           w.y = pk2(x4.z * rinv * g4.z * (1.f + sc.z) + sh.z, x4.w * rinv * g4.w * (1.f + sc.w) + sh.w);
;           *(uint2*)(h + wimg_off(row, e, DM)) = w;
;         }
	v_mul_f32_e32 v220, v97, v97
	v_mul_f32_e32 v224, v113, v113
	v_fmac_f32_e32 v220, v96, v96
	v_fmac_f32_e32 v224, v112, v112
	v_fmac_f32_e32 v220, v98, v98
	v_fmac_f32_e32 v224, v114, v114
	v_fmac_f32_e32 v220, v99, v99
	v_fmac_f32_e32 v224, v115, v115
	v_mul_f32_e32 v221, v101, v101
	v_mul_f32_e32 v225, v117, v117
	v_fmac_f32_e32 v221, v100, v100
	v_fmac_f32_e32 v225, v116, v116
	v_fmac_f32_e32 v221, v102, v102
	v_fmac_f32_e32 v225, v118, v118
	v_fmac_f32_e32 v221, v103, v103
	v_fmac_f32_e32 v225, v119, v119
	v_mul_f32_e32 v222, v105, v105
	v_mul_f32_e32 v226, v121, v121
	v_fmac_f32_e32 v222, v104, v104
	v_fmac_f32_e32 v226, v120, v120
	v_fmac_f32_e32 v222, v106, v106
	v_fmac_f32_e32 v226, v122, v122
	v_fmac_f32_e32 v222, v107, v107
	v_fmac_f32_e32 v226, v123, v123
	v_mul_f32_e32 v223, v109, v109
	v_mul_f32_e32 v227, v125, v125
	v_fmac_f32_e32 v223, v108, v108
	v_fmac_f32_e32 v227, v124, v124
	v_fmac_f32_e32 v223, v110, v110
	v_fmac_f32_e32 v227, v126, v126
	v_fmac_f32_e32 v223, v111, v111
	v_fmac_f32_e32 v227, v127, v127
	v_add_f32_e32 v228, v220, v221
	v_add_f32_e32 v229, v224, v225
	v_add_f32_e32 v228, v228, v222
	v_add_f32_e32 v229, v229, v226
	v_add_f32_e32 v228, v228, v223
	v_add_f32_e32 v229, v229, v227
	ds_bpermute_b32 v230, v236, v228
	ds_bpermute_b32 v231, v236, v229
	s_waitcnt lgkmcnt(0)
	v_add_f32_e32 v228, v228, v230
	v_add_f32_e32 v229, v229, v231
	ds_bpermute_b32 v230, v237, v228
	ds_bpermute_b32 v231, v237, v229
	s_waitcnt lgkmcnt(0)
	v_add_f32_e32 v228, v228, v230
	v_add_f32_e32 v229, v229, v231
	ds_bpermute_b32 v230, v238, v228
	ds_bpermute_b32 v231, v238, v229
	s_waitcnt lgkmcnt(0)
	v_add_f32_e32 v228, v228, v230
	v_add_f32_e32 v229, v229, v231
	ds_bpermute_b32 v230, v239, v228
	ds_bpermute_b32 v231, v239, v229
	s_waitcnt lgkmcnt(0)
	v_add_f32_e32 v228, v228, v230
	v_add_f32_e32 v229, v229, v231
	ds_bpermute_b32 v230, v240, v228
	ds_bpermute_b32 v231, v240, v229
	s_waitcnt lgkmcnt(0)
	v_add_f32_e32 v228, v228, v230
	v_add_f32_e32 v229, v229, v231
	ds_bpermute_b32 v230, v241, v228
	ds_bpermute_b32 v231, v241, v229
	s_waitcnt lgkmcnt(0)
	v_add_f32_e32 v228, v228, v230
	v_add_f32_e32 v229, v229, v231
	v_fma_f32 v228, v228, s26, v162
	v_fma_f32 v229, v229, s26, v162
	v_rsq_f32_e32 v232, v228
	v_rsq_f32_e32 v233, v229
	s_nop 0
	v_mul_f32_e32 v96, v96, v232
	v_mul_f32_e32 v97, v97, v232
	v_mul_f32_e32 v98, v98, v232
	v_mul_f32_e32 v99, v99, v232
	v_mul_f32_e32 v96, v128, v96
	v_mul_f32_e32 v97, v129, v97
	v_mul_f32_e32 v98, v130, v98
	v_mul_f32_e32 v99, v131, v99
	v_fma_f32 v96, v96, v204, v144
	v_fma_f32 v97, v97, v205, v145
	v_fma_f32 v98, v98, v206, v146
	v_fma_f32 v99, v99, v207, v147
	v_cvt_pk_bf16_f32 v234, v96, v97
	v_cvt_pk_bf16_f32 v235, v98, v99
	s_nop 0
	global_store_dwordx2 v243, v[234:235], s[18:19] offset:3072
	v_mul_f32_e32 v100, v100, v232
	v_mul_f32_e32 v101, v101, v232
	v_mul_f32_e32 v102, v102, v232
	v_mul_f32_e32 v103, v103, v232
	v_mul_f32_e32 v100, v132, v100
	v_mul_f32_e32 v101, v133, v101
	v_mul_f32_e32 v102, v134, v102
	v_mul_f32_e32 v103, v135, v103
	v_fma_f32 v100, v100, v208, v148
	v_fma_f32 v101, v101, v209, v149
	v_fma_f32 v102, v102, v210, v150
	v_fma_f32 v103, v103, v211, v151
	v_cvt_pk_bf16_f32 v234, v100, v101
	v_cvt_pk_bf16_f32 v235, v102, v103
	s_nop 0
	global_store_dwordx2 v243, v[234:235], s[20:21] offset:3072
	v_mul_f32_e32 v104, v104, v232
	v_mul_f32_e32 v105, v105, v232
	v_mul_f32_e32 v106, v106, v232
	v_mul_f32_e32 v107, v107, v232
	v_mul_f32_e32 v104, v136, v104
	v_mul_f32_e32 v105, v137, v105
	v_mul_f32_e32 v106, v138, v106
	v_mul_f32_e32 v107, v139, v107
	v_fma_f32 v104, v104, v212, v152
	v_fma_f32 v105, v105, v213, v153
	v_fma_f32 v106, v106, v214, v154
	v_fma_f32 v107, v107, v215, v155
	v_cvt_pk_bf16_f32 v234, v104, v105
	v_cvt_pk_bf16_f32 v235, v106, v107
	s_nop 0
	global_store_dwordx2 v243, v[234:235], s[22:23] offset:3072
	v_mul_f32_e32 v108, v108, v232
	v_mul_f32_e32 v109, v109, v232
	v_mul_f32_e32 v110, v110, v232
	v_mul_f32_e32 v111, v111, v232
	v_mul_f32_e32 v108, v140, v108
	v_mul_f32_e32 v109, v141, v109
	v_mul_f32_e32 v110, v142, v110
	v_mul_f32_e32 v111, v143, v111
	v_fma_f32 v108, v108, v216, v156
	v_fma_f32 v109, v109, v217, v157
	v_fma_f32 v110, v110, v218, v158
	v_fma_f32 v111, v111, v219, v159
	v_cvt_pk_bf16_f32 v234, v108, v109
	v_cvt_pk_bf16_f32 v235, v110, v111
	s_nop 0
	global_store_dwordx2 v243, v[234:235], s[24:25] offset:3072
	v_mul_f32_e32 v112, v112, v233
	v_mul_f32_e32 v113, v113, v233
	v_mul_f32_e32 v114, v114, v233
	v_mul_f32_e32 v115, v115, v233
	v_mul_f32_e32 v112, v128, v112
	v_mul_f32_e32 v113, v129, v113
	v_mul_f32_e32 v114, v130, v114
	v_mul_f32_e32 v115, v131, v115
	v_fma_f32 v112, v112, v204, v144
	v_fma_f32 v113, v113, v205, v145
	v_fma_f32 v114, v114, v206, v146
	v_fma_f32 v115, v115, v207, v147
	v_cvt_pk_bf16_f32 v234, v112, v113
	v_cvt_pk_bf16_f32 v235, v114, v115
	s_nop 0
	global_store_dwordx2 v244, v[234:235], s[18:19] offset:3072
	v_mul_f32_e32 v116, v116, v233
	v_mul_f32_e32 v117, v117, v233
	v_mul_f32_e32 v118, v118, v233
	v_mul_f32_e32 v119, v119, v233
	v_mul_f32_e32 v116, v132, v116
	v_mul_f32_e32 v117, v133, v117
	v_mul_f32_e32 v118, v134, v118
	v_mul_f32_e32 v119, v135, v119
	v_fma_f32 v116, v116, v208, v148
	v_fma_f32 v117, v117, v209, v149
	v_fma_f32 v118, v118, v210, v150
	v_fma_f32 v119, v119, v211, v151
	v_cvt_pk_bf16_f32 v234, v116, v117
	v_cvt_pk_bf16_f32 v235, v118, v119
	s_nop 0
	global_store_dwordx2 v244, v[234:235], s[20:21] offset:3072
	v_mul_f32_e32 v120, v120, v233
	v_mul_f32_e32 v121, v121, v233
	v_mul_f32_e32 v122, v122, v233
	v_mul_f32_e32 v123, v123, v233
	v_mul_f32_e32 v120, v136, v120
	v_mul_f32_e32 v121, v137, v121
	v_mul_f32_e32 v122, v138, v122
	v_mul_f32_e32 v123, v139, v123
	v_fma_f32 v120, v120, v212, v152
	v_fma_f32 v121, v121, v213, v153
	v_fma_f32 v122, v122, v214, v154
	v_fma_f32 v123, v123, v215, v155
	v_cvt_pk_bf16_f32 v234, v120, v121
	v_cvt_pk_bf16_f32 v235, v122, v123
	s_nop 0
	global_store_dwordx2 v244, v[234:235], s[22:23] offset:3072
	v_mul_f32_e32 v124, v124, v233
	v_mul_f32_e32 v125, v125, v233
	v_mul_f32_e32 v126, v126, v233
	v_mul_f32_e32 v127, v127, v233
	v_mul_f32_e32 v124, v140, v124
	v_mul_f32_e32 v125, v141, v125
	v_mul_f32_e32 v126, v142, v126
	v_mul_f32_e32 v127, v143, v127
	v_fma_f32 v124, v124, v216, v156
	v_fma_f32 v125, v125, v217, v157
	v_fma_f32 v126, v126, v218, v158
	v_fma_f32 v127, v127, v219, v159
	v_cvt_pk_bf16_f32 v234, v124, v125
	v_cvt_pk_bf16_f32 v235, v126, v127
	s_nop 0
	global_store_dwordx2 v244, v[234:235], s[24:25] offset:3072
	s_branch .LBB0_235

; DI void norm_unit(const Params& p, int layer, int half, int nu, int tid) { norm_rows(p, layer, half * HROWS + nu * 64, 64, 0, 8, tid); }
; #define otid() otid_(wbase)
; DI void norm_rows(const Params& p, int layer, int row0, int nrows, int wstart, int wstride, int tid) {
;     ...
;   for (int rowa = row0 + wstart + wid; rowa < row0 + nrows; rowa += 2 * wstride) {
;     const int rowb = (rowa + wstride < row0 + nrows) ? rowa + wstride : rowa;
;     float4 va[4], vb[4]; float sa = 0.f, sb = 0.f;
; #pragma unroll
;     for (int i = 0; i < 4; ++i) { va[i] = *(const float4*)(xin + (size_t)rowa * DM + i * 256 + lane * 4); vb[i] = *(const float4*)(xin + (size_t)rowb * DM + i * 256 + lane * 4); }
; #pragma unroll
;     for (int i = 0; i < 4; ++i) { sa += va[i].x * va[i].x + va[i].y * va[i].y + va[i].z * va[i].z + va[i].w * va[i].w; sb += vb[i].x * vb[i].x + vb[i].y * vb[i].y + vb[i].z * vb[i].z + vb[i].w * vb[i].w; }
; __global__ void __launch_bounds__(NTHR) mega(Params p) {
;     ...
;           int u = u0;
;           if (u >= 1344 + n_fill) break;
;           if (u >= 448 && u < 448 + n_fill) { norm_unit(p, layer + 1, 0, u - 448, otid()); continue; }
;           if (u >= 448) u -= n_fill;
.LBB0_622:
	v_readlane_b32 s0, v254, 61
	s_and_b64 vcc, exec, s[4:5]
	v_readlane_b32 s1, v254, 62
	s_cbranch_vccz .LBB0_411
	v_mov_b32_e32 v0, v163
	s_nop 0
	v_ashrrev_i32_e32 v1, 6, v0
	v_cmp_gt_i32_e32 vcc, 64, v1
	s_and_saveexec_b64 s[0:1], vcc
	s_cbranch_execz .LBB0_410
	v_readlane_b32 s8, v254, 35
	v_readlane_b32 s9, v254, 36
	s_and_b64 vcc, exec, s[8:9]
	s_cbranch_vccz .Lp4n_orig
	s_lshl_b32 s17, s23, 6
	s_addk_i32 s17, 0x9000
	v_readlane_b32 s6, v254, 39
	v_readlane_b32 s7, v254, 40
	v_readlane_b32 s8, v252, 22
	v_readlane_b32 s9, v252, 23
	v_readlane_b32 s16, v254, 37
	v_readlane_b32 s12, v252, 48
	v_readlane_b32 s13, v252, 49
	s_lshl_b32 s15, s17, 12
	s_add_u32 s4, s36, s15
	s_addc_u32 s5, s37, 0
	s_add_u32 s6, s6, 0
	s_addc_u32 s7, s7, 0
	s_lshr_b32 s15, s17, 13
	s_add_i32 s15, s15, s16
	s_mul_i32 s15, s15, 0x3000
	s_add_u32 s8, s8, s15
	s_addc_u32 s9, s9, 0
	s_add_u32 s10, s8, 0x1000
	s_addc_u32 s11, s9, 0
	s_lshr_b32 s15, s17, 7
	s_lshl_b32 s15, s15, 18
	s_bfe_u32 s16, s17, 0x10006
	s_lshl_b32 s16, s16, 12
	s_add_u32 s15, s15, s16
	s_add_u32 s12, s12, s15
	s_addc_u32 s13, s13, 0
	v_and_b32_e32 v245, 63, v163
	v_lshrrev_b32_e32 v246, 6, v163
	v_lshlrev_b32_e32 v247, 2, v245
	v_xor_b32_e32 v236, 0x80, v247
	v_xor_b32_e32 v237, 0x40, v247
	v_xor_b32_e32 v238, 0x20, v247
	v_xor_b32_e32 v239, 0x10, v247
	v_xor_b32_e32 v240, 0x8, v247
	v_xor_b32_e32 v241, 0x4, v247
	v_lshlrev_b32_e32 v245, 4, v245
	v_lshl_add_u32 v242, v246, 12, v245
	v_and_b32_e32 v248, 63, v163
	v_lshrrev_b32_e32 v249, 3, v248
	v_and_b32_e32 v248, 7, v248
	v_lshlrev_b32_e32 v248, 3, v248
	v_lshlrev_b32_e32 v249, 13, v249
	v_lshl_add_u32 v249, v246, 6, v249
	v_add_u32_e32 v243, v249, v248
	v_xor_b32_e32 v248, 32, v248
	v_add_u32_e32 v244, v249, v248
	v_add_u32_e32 v244, 0x200, v244
	global_load_dwordx4 v[128:131], v245, s[6:7] offset:0
	global_load_dwordx4 v[132:135], v245, s[6:7] offset:1024
	global_load_dwordx4 v[136:139], v245, s[6:7] offset:2048
	global_load_dwordx4 v[140:143], v245, s[6:7] offset:3072
	global_load_dwordx4 v[144:147], v245, s[8:9] offset:0
	global_load_dwordx4 v[148:151], v245, s[8:9] offset:1024
	global_load_dwordx4 v[152:155], v245, s[8:9] offset:2048
	global_load_dwordx4 v[156:159], v245, s[8:9] offset:3072
	global_load_dwordx4 v[204:207], v245, s[10:11] offset:0
	global_load_dwordx4 v[208:211], v245, s[10:11] offset:1024
	global_load_dwordx4 v[212:215], v245, s[10:11] offset:2048
	global_load_dwordx4 v[216:219], v245, s[10:11] offset:3072
	global_load_dwordx4 v[0:3], v242, s[4:5] offset:0
	global_load_dwordx4 v[4:7], v242, s[4:5] offset:1024
	global_load_dwordx4 v[8:11], v242, s[4:5] offset:2048
	global_load_dwordx4 v[12:15], v242, s[4:5] offset:3072
	s_add_u32 s4, s4, 0x8000
	s_addc_u32 s5, s5, 0
	global_load_dwordx4 v[16:19], v242, s[4:5] offset:0
	global_load_dwordx4 v[20:23], v242, s[4:5] offset:1024
	global_load_dwordx4 v[24:27], v242, s[4:5] offset:2048
	global_load_dwordx4 v[28:31], v242, s[4:5] offset:3072
	s_add_u32 s4, s4, 0x8000
	s_addc_u32 s5, s5, 0
	global_load_dwordx4 v[32:35], v242, s[4:5] offset:0
	global_load_dwordx4 v[36:39], v242, s[4:5] offset:1024
	global_load_dwordx4 v[40:43], v242, s[4:5] offset:2048
	global_load_dwordx4 v[44:47], v242, s[4:5] offset:3072
	s_add_u32 s4, s4, 0x8000
	s_addc_u32 s5, s5, 0
	global_load_dwordx4 v[48:51], v242, s[4:5] offset:0
	global_load_dwordx4 v[52:55], v242, s[4:5] offset:1024
	global_load_dwordx4 v[56:59], v242, s[4:5] offset:2048
	global_load_dwordx4 v[60:63], v242, s[4:5] offset:3072
	s_add_u32 s4, s4, 0x8000
	s_addc_u32 s5, s5, 0
	global_load_dwordx4 v[64:67], v242, s[4:5] offset:0
	global_load_dwordx4 v[68:71], v242, s[4:5] offset:1024
	global_load_dwordx4 v[72:75], v242, s[4:5] offset:2048
	global_load_dwordx4 v[76:79], v242, s[4:5] offset:3072
	s_add_u32 s4, s4, 0x8000
	s_addc_u32 s5, s5, 0
	global_load_dwordx4 v[80:83], v242, s[4:5] offset:0
	global_load_dwordx4 v[84:87], v242, s[4:5] offset:1024
	global_load_dwordx4 v[88:91], v242, s[4:5] offset:2048
	global_load_dwordx4 v[92:95], v242, s[4:5] offset:3072
	s_add_u32 s4, s4, 0x8000
	s_addc_u32 s5, s5, 0
	global_load_dwordx4 v[96:99], v242, s[4:5] offset:0
	global_load_dwordx4 v[100:103], v242, s[4:5] offset:1024
	global_load_dwordx4 v[104:107], v242, s[4:5] offset:2048
	global_load_dwordx4 v[108:111], v242, s[4:5] offset:3072
	s_add_u32 s4, s4, 0x8000
	s_addc_u32 s5, s5, 0
	global_load_dwordx4 v[112:115], v242, s[4:5] offset:0
	global_load_dwordx4 v[116:119], v242, s[4:5] offset:1024
	global_load_dwordx4 v[120:123], v242, s[4:5] offset:2048
	global_load_dwordx4 v[124:127], v242, s[4:5] offset:3072
	v_add_u32_e32 v248, 0x10000, v243
	v_add_u32_e32 v251, 0x10000, v244
	v_add_u32_e32 v249, 0x20000, v243
	v_add_u32_e32 v246, 0x20000, v244
	v_add_u32_e32 v250, 0x30000, v243
	v_add_u32_e32 v247, 0x30000, v244
	s_mov_b32 s14, 0x3a800000
	s_waitcnt vmcnt(24)
; DI unsigned pk2(float lo, float hi) { unsigned r; asm volatile("v_cvt_pk_bf16_f32 %0, %1, %2" : "=v"(r) : "v"(lo), "v"(hi)); return r; }
; DI float shx(float v, int m, int lane) { return __int_as_float(__builtin_amdgcn_ds_bpermute((lane ^ m) << 2, __float_as_int(v))); }
; DI void norm_rows(const Params& p, int layer, int row0, int nrows, int wstart, int wstride, int tid) {
;     ...
;     for (int i = 0; i < 4; ++i) { va[i] = *(const float4*)(xin + (size_t)rowa * DM + i * 256 + lane * 4); vb[i] = *(const float4*)(xin + (size_t)rowb * DM + i * 256 + lane * 4); }
; #pragma unroll
;     for (int i = 0; i < 4; ++i) { sa += va[i].x * va[i].x + va[i].y * va[i].y + va[i].z * va[i].z + va[i].w * va[i].w; sb += vb[i].x * vb[i].x + vb[i].y * vb[i].y + vb[i].z * vb[i].z + vb[i].w * vb[i].w; }
; #pragma unroll
;     for (int o = 32; o >= 1; o >>= 1) { sa += shx(sa, o, lane); sb += shx(sb, o, lane); }
; #pragma unroll
;     for (int rr = 0; rr < 2; ++rr) {
;       const int row = rr ? rowb : rowa; const float rinv = rsqrtf((rr ? sb : sa) * (1.0f / 1024.0f) + EPS);
;       if (layer < NLAYER) {
;         const int b = row >> 13; const float* md = modb + (size_t)(layer * 4 + b) * 3072; const float* g = p.norm_g + layer * 1024;
; #pragma unroll
;         for (int i = 0; i < 4; ++i) {
;           const float4 x4 = rr ? vb[i] : va[i];
;           const int e = i * 256 + lane * 4;
;           const float4 g4 = *(const float4*)(g + e), sh = *(const float4*)(md + e), sc = *(const float4*)(md + 1024 + e);
;           uint2 w;
;           w.x = pk2(x4.x * rinv * g4.x * (1.f + sc.x) + sh.x, x4.y * rinv * g4.y * (1.f + sc.y) + sh.y);
;           w.y = pk2(x4.z * rinv * g4.z * (1.f + sc.z) + sh.z, x4.w * rinv * g4.w * (1.f + sc.w) + sh.w);
;           *(uint2*)(h + wimg_off(row, e, DM)) = w;
	v_add_f32_e32 v204, 1.0, v204
	v_add_f32_e32 v205, 1.0, v205
	v_add_f32_e32 v206, 1.0, v206
	v_add_f32_e32 v207, 1.0, v207
	v_add_f32_e32 v208, 1.0, v208
	v_add_f32_e32 v209, 1.0, v209
	v_add_f32_e32 v210, 1.0, v210
	v_add_f32_e32 v211, 1.0, v211
	v_add_f32_e32 v212, 1.0, v212
	v_add_f32_e32 v213, 1.0, v213
	v_add_f32_e32 v214, 1.0, v214
	v_add_f32_e32 v215, 1.0, v215
	v_add_f32_e32 v216, 1.0, v216
	v_add_f32_e32 v217, 1.0, v217
	v_add_f32_e32 v218, 1.0, v218
	v_add_f32_e32 v219, 1.0, v219
	v_mul_f32_e32 v220, v1, v1
	v_mul_f32_e32 v224, v17, v17
	v_fmac_f32_e32 v220, v0, v0
	v_fmac_f32_e32 v224, v16, v16
	v_fmac_f32_e32 v220, v2, v2
	v_fmac_f32_e32 v224, v18, v18
	v_fmac_f32_e32 v220, v3, v3
	v_fmac_f32_e32 v224, v19, v19
	v_mul_f32_e32 v221, v5, v5
	v_mul_f32_e32 v225, v21, v21
	v_fmac_f32_e32 v221, v4, v4
	v_fmac_f32_e32 v225, v20, v20
	v_fmac_f32_e32 v221, v6, v6
	v_fmac_f32_e32 v225, v22, v22
	v_fmac_f32_e32 v221, v7, v7
	v_fmac_f32_e32 v225, v23, v23
	v_mul_f32_e32 v222, v9, v9
	v_mul_f32_e32 v226, v25, v25
	v_fmac_f32_e32 v222, v8, v8
	v_fmac_f32_e32 v226, v24, v24
	v_fmac_f32_e32 v222, v10, v10
	v_fmac_f32_e32 v226, v26, v26
	v_fmac_f32_e32 v222, v11, v11
	v_fmac_f32_e32 v226, v27, v27
	v_mul_f32_e32 v223, v13, v13
	v_mul_f32_e32 v227, v29, v29
	v_fmac_f32_e32 v223, v12, v12
	v_fmac_f32_e32 v227, v28, v28
	v_fmac_f32_e32 v223, v14, v14
	v_fmac_f32_e32 v227, v30, v30
	v_fmac_f32_e32 v223, v15, v15
	v_fmac_f32_e32 v227, v31, v31
	v_add_f32_e32 v228, v220, v221
	v_add_f32_e32 v229, v224, v225
	v_add_f32_e32 v228, v228, v222
	v_add_f32_e32 v229, v229, v226
	v_add_f32_e32 v228, v228, v223
	v_add_f32_e32 v229, v229, v227
	ds_bpermute_b32 v230, v236, v228
	ds_bpermute_b32 v231, v236, v229
	s_waitcnt lgkmcnt(0)
	v_add_f32_e32 v228, v228, v230
	v_add_f32_e32 v229, v229, v231
	ds_bpermute_b32 v230, v237, v228
	ds_bpermute_b32 v231, v237, v229
	s_waitcnt lgkmcnt(0)
	v_add_f32_e32 v228, v228, v230
	v_add_f32_e32 v229, v229, v231
	ds_bpermute_b32 v230, v238, v228
	ds_bpermute_b32 v231, v238, v229
	s_waitcnt lgkmcnt(0)
	v_add_f32_e32 v228, v228, v230
	v_add_f32_e32 v229, v229, v231
	ds_bpermute_b32 v230, v239, v228
	ds_bpermute_b32 v231, v239, v229
	s_waitcnt lgkmcnt(0)
	v_add_f32_e32 v228, v228, v230
	v_add_f32_e32 v229, v229, v231
	ds_bpermute_b32 v230, v240, v228
	ds_bpermute_b32 v231, v240, v229
	s_waitcnt lgkmcnt(0)
	v_add_f32_e32 v228, v228, v230
	v_add_f32_e32 v229, v229, v231
	ds_bpermute_b32 v230, v241, v228
	ds_bpermute_b32 v231, v241, v229
	s_waitcnt lgkmcnt(0)
	v_add_f32_e32 v228, v228, v230
	v_add_f32_e32 v229, v229, v231
	v_fma_f32 v228, v228, s14, v162
	v_fma_f32 v229, v229, s14, v162
	v_rsq_f32_e32 v232, v228
	v_rsq_f32_e32 v233, v229
	s_nop 0
	v_mul_f32_e32 v0, v0, v232
	v_mul_f32_e32 v1, v1, v232
	v_mul_f32_e32 v2, v2, v232
	v_mul_f32_e32 v3, v3, v232
	v_mul_f32_e32 v0, v128, v0
	v_mul_f32_e32 v1, v129, v1
	v_mul_f32_e32 v2, v130, v2
	v_mul_f32_e32 v3, v131, v3
	v_fma_f32 v0, v0, v204, v144
	v_fma_f32 v1, v1, v205, v145
	v_fma_f32 v2, v2, v206, v146
	v_fma_f32 v3, v3, v207, v147
	v_cvt_pk_bf16_f32 v234, v0, v1
	v_cvt_pk_bf16_f32 v235, v2, v3
	s_nop 0
	global_store_dwordx2 v243, v[234:235], s[12:13] offset:0
	v_mul_f32_e32 v4, v4, v232
	v_mul_f32_e32 v5, v5, v232
	v_mul_f32_e32 v6, v6, v232
	v_mul_f32_e32 v7, v7, v232
	v_mul_f32_e32 v4, v132, v4
	v_mul_f32_e32 v5, v133, v5
	v_mul_f32_e32 v6, v134, v6
	v_mul_f32_e32 v7, v135, v7
	v_fma_f32 v4, v4, v208, v148
	v_fma_f32 v5, v5, v209, v149
	v_fma_f32 v6, v6, v210, v150
	v_fma_f32 v7, v7, v211, v151
	v_cvt_pk_bf16_f32 v234, v4, v5
	v_cvt_pk_bf16_f32 v235, v6, v7
	s_nop 0
	global_store_dwordx2 v248, v[234:235], s[12:13] offset:0
	v_mul_f32_e32 v8, v8, v232
	v_mul_f32_e32 v9, v9, v232
	v_mul_f32_e32 v10, v10, v232
	v_mul_f32_e32 v11, v11, v232
	v_mul_f32_e32 v8, v136, v8
	v_mul_f32_e32 v9, v137, v9
	v_mul_f32_e32 v10, v138, v10
	v_mul_f32_e32 v11, v139, v11
	v_fma_f32 v8, v8, v212, v152
	v_fma_f32 v9, v9, v213, v153
	v_fma_f32 v10, v10, v214, v154
	v_fma_f32 v11, v11, v215, v155
	v_cvt_pk_bf16_f32 v234, v8, v9
	v_cvt_pk_bf16_f32 v235, v10, v11
	s_nop 0
	global_store_dwordx2 v249, v[234:235], s[12:13] offset:0
	v_mul_f32_e32 v12, v12, v232
	v_mul_f32_e32 v13, v13, v232
	v_mul_f32_e32 v14, v14, v232
	v_mul_f32_e32 v15, v15, v232
	v_mul_f32_e32 v12, v140, v12
	v_mul_f32_e32 v13, v141, v13
	v_mul_f32_e32 v14, v142, v14
	v_mul_f32_e32 v15, v143, v15
	v_fma_f32 v12, v12, v216, v156
	v_fma_f32 v13, v13, v217, v157
	v_fma_f32 v14, v14, v218, v158
	v_fma_f32 v15, v15, v219, v159
	v_cvt_pk_bf16_f32 v234, v12, v13
	v_cvt_pk_bf16_f32 v235, v14, v15
	s_nop 0
	global_store_dwordx2 v250, v[234:235], s[12:13] offset:0
	v_mul_f32_e32 v16, v16, v233
	v_mul_f32_e32 v17, v17, v233
	v_mul_f32_e32 v18, v18, v233
	v_mul_f32_e32 v19, v19, v233
	v_mul_f32_e32 v16, v128, v16
	v_mul_f32_e32 v17, v129, v17
	v_mul_f32_e32 v18, v130, v18
	v_mul_f32_e32 v19, v131, v19
	v_fma_f32 v16, v16, v204, v144
	v_fma_f32 v17, v17, v205, v145
	v_fma_f32 v18, v18, v206, v146
	v_fma_f32 v19, v19, v207, v147
	v_cvt_pk_bf16_f32 v234, v16, v17
	v_cvt_pk_bf16_f32 v235, v18, v19
	s_nop 0
	global_store_dwordx2 v244, v[234:235], s[12:13] offset:0
	v_mul_f32_e32 v20, v20, v233
	v_mul_f32_e32 v21, v21, v233
	v_mul_f32_e32 v22, v22, v233
	v_mul_f32_e32 v23, v23, v233
	v_mul_f32_e32 v20, v132, v20
	v_mul_f32_e32 v21, v133, v21
	v_mul_f32_e32 v22, v134, v22
	v_mul_f32_e32 v23, v135, v23
	v_fma_f32 v20, v20, v208, v148
	v_fma_f32 v21, v21, v209, v149
	v_fma_f32 v22, v22, v210, v150
	v_fma_f32 v23, v23, v211, v151
	v_cvt_pk_bf16_f32 v234, v20, v21
	v_cvt_pk_bf16_f32 v235, v22, v23
	s_nop 0
	global_store_dwordx2 v251, v[234:235], s[12:13] offset:0
	v_mul_f32_e32 v24, v24, v233
	v_mul_f32_e32 v25, v25, v233
	v_mul_f32_e32 v26, v26, v233
	v_mul_f32_e32 v27, v27, v233
	v_mul_f32_e32 v24, v136, v24
	v_mul_f32_e32 v25, v137, v25
	v_mul_f32_e32 v26, v138, v26
	v_mul_f32_e32 v27, v139, v27
	v_fma_f32 v24, v24, v212, v152
	v_fma_f32 v25, v25, v213, v153
	v_fma_f32 v26, v26, v214, v154
	v_fma_f32 v27, v27, v215, v155
	v_cvt_pk_bf16_f32 v234, v24, v25
	v_cvt_pk_bf16_f32 v235, v26, v27
	s_nop 0
	global_store_dwordx2 v246, v[234:235], s[12:13] offset:0
	v_mul_f32_e32 v28, v28, v233
	v_mul_f32_e32 v29, v29, v233
	v_mul_f32_e32 v30, v30, v233
	v_mul_f32_e32 v31, v31, v233
	v_mul_f32_e32 v28, v140, v28
	v_mul_f32_e32 v29, v141, v29
	v_mul_f32_e32 v30, v142, v30
	v_mul_f32_e32 v31, v143, v31
	v_fma_f32 v28, v28, v216, v156
	v_fma_f32 v29, v29, v217, v157
	v_fma_f32 v30, v30, v218, v158
	v_fma_f32 v31, v31, v219, v159
	v_cvt_pk_bf16_f32 v234, v28, v29
	v_cvt_pk_bf16_f32 v235, v30, v31
	s_nop 0
	global_store_dwordx2 v247, v[234:235], s[12:13] offset:0
	s_waitcnt vmcnt(24)
; DI unsigned pk2(float lo, float hi) { unsigned r; asm volatile("v_cvt_pk_bf16_f32 %0, %1, %2" : "=v"(r) : "v"(lo), "v"(hi)); return r; }
; DI float shx(float v, int m, int lane) { return __int_as_float(__builtin_amdgcn_ds_bpermute((lane ^ m) << 2, __float_as_int(v))); }
; DI void norm_rows(const Params& p, int layer, int row0, int nrows, int wstart, int wstride, int tid) {
;     ...
;     for (int i = 0; i < 4; ++i) { sa += va[i].x * va[i].x + va[i].y * va[i].y + va[i].z * va[i].z + va[i].w * va[i].w; sb += vb[i].x * vb[i].x + vb[i].y * vb[i].y + vb[i].z * vb[i].z + vb[i].w * vb[i].w; }
; #pragma unroll
;     for (int o = 32; o >= 1; o >>= 1) { sa += shx(sa, o, lane); sb += shx(sb, o, lane); }
; #pragma unroll
;     for (int rr = 0; rr < 2; ++rr) {
;       const int row = rr ? rowb : rowa; const float rinv = rsqrtf((rr ? sb : sa) * (1.0f / 1024.0f) + EPS);
;       if (layer < NLAYER) {
;         const int b = row >> 13; const float* md = modb + (size_t)(layer * 4 + b) * 3072; const float* g = p.norm_g + layer * 1024;
; #pragma unroll
;         for (int i = 0; i < 4; ++i) {
;           const float4 x4 = rr ? vb[i] : va[i];
;           const int e = i * 256 + lane * 4;
;           const float4 g4 = *(const float4*)(g + e), sh = *(const float4*)(md + e), sc = *(const float4*)(md + 1024 + e);
;           uint2 w;
;           w.x = pk2(x4.x * rinv * g4.x * (1.f + sc.x) + sh.x, x4.y * rinv * g4.y * (1.f + sc.y) + sh.y);
;           w.y = pk2(x4.z * rinv * g4.z * (1.f + sc.z) + sh.z, x4.w * rinv * g4.w * (1.f + sc.w) + sh.w);
;           *(uint2*)(h + wimg_off(row, e, DM)) = w;
	v_mul_f32_e32 v220, v33, v33
	v_mul_f32_e32 v224, v49, v49
	v_fmac_f32_e32 v220, v32, v32
	v_fmac_f32_e32 v224, v48, v48
	v_fmac_f32_e32 v220, v34, v34
	v_fmac_f32_e32 v224, v50, v50
	v_fmac_f32_e32 v220, v35, v35
	v_fmac_f32_e32 v224, v51, v51
	v_mul_f32_e32 v221, v37, v37
	v_mul_f32_e32 v225, v53, v53
	v_fmac_f32_e32 v221, v36, v36
	v_fmac_f32_e32 v225, v52, v52
	v_fmac_f32_e32 v221, v38, v38
	v_fmac_f32_e32 v225, v54, v54
	v_fmac_f32_e32 v221, v39, v39
	v_fmac_f32_e32 v225, v55, v55
	v_mul_f32_e32 v222, v41, v41
	v_mul_f32_e32 v226, v57, v57
	v_fmac_f32_e32 v222, v40, v40
	v_fmac_f32_e32 v226, v56, v56
	v_fmac_f32_e32 v222, v42, v42
	v_fmac_f32_e32 v226, v58, v58
	v_fmac_f32_e32 v222, v43, v43
	v_fmac_f32_e32 v226, v59, v59
	v_mul_f32_e32 v223, v45, v45
	v_mul_f32_e32 v227, v61, v61
	v_fmac_f32_e32 v223, v44, v44
	v_fmac_f32_e32 v227, v60, v60
	v_fmac_f32_e32 v223, v46, v46
	v_fmac_f32_e32 v227, v62, v62
	v_fmac_f32_e32 v223, v47, v47
	v_fmac_f32_e32 v227, v63, v63
	v_add_f32_e32 v228, v220, v221
	v_add_f32_e32 v229, v224, v225
	v_add_f32_e32 v228, v228, v222
	v_add_f32_e32 v229, v229, v226
	v_add_f32_e32 v228, v228, v223
	v_add_f32_e32 v229, v229, v227
	ds_bpermute_b32 v230, v236, v228
	ds_bpermute_b32 v231, v236, v229
	s_waitcnt lgkmcnt(0)
	v_add_f32_e32 v228, v228, v230
	v_add_f32_e32 v229, v229, v231
	ds_bpermute_b32 v230, v237, v228
	ds_bpermute_b32 v231, v237, v229
	s_waitcnt lgkmcnt(0)
	v_add_f32_e32 v228, v228, v230
	v_add_f32_e32 v229, v229, v231
	ds_bpermute_b32 v230, v238, v228
	ds_bpermute_b32 v231, v238, v229
	s_waitcnt lgkmcnt(0)
	v_add_f32_e32 v228, v228, v230
	v_add_f32_e32 v229, v229, v231
	ds_bpermute_b32 v230, v239, v228
	ds_bpermute_b32 v231, v239, v229
	s_waitcnt lgkmcnt(0)
	v_add_f32_e32 v228, v228, v230
	v_add_f32_e32 v229, v229, v231
	ds_bpermute_b32 v230, v240, v228
	ds_bpermute_b32 v231, v240, v229
	s_waitcnt lgkmcnt(0)
	v_add_f32_e32 v228, v228, v230
	v_add_f32_e32 v229, v229, v231
	ds_bpermute_b32 v230, v241, v228
	ds_bpermute_b32 v231, v241, v229
	s_waitcnt lgkmcnt(0)
	v_add_f32_e32 v228, v228, v230
	v_add_f32_e32 v229, v229, v231
	v_fma_f32 v228, v228, s14, v162
	v_fma_f32 v229, v229, s14, v162
	v_rsq_f32_e32 v232, v228
	v_rsq_f32_e32 v233, v229
	s_nop 0
	v_mul_f32_e32 v32, v32, v232
	v_mul_f32_e32 v33, v33, v232
	v_mul_f32_e32 v34, v34, v232
	v_mul_f32_e32 v35, v35, v232
	v_mul_f32_e32 v32, v128, v32
	v_mul_f32_e32 v33, v129, v33
	v_mul_f32_e32 v34, v130, v34
	v_mul_f32_e32 v35, v131, v35
	v_fma_f32 v32, v32, v204, v144
	v_fma_f32 v33, v33, v205, v145
	v_fma_f32 v34, v34, v206, v146
	v_fma_f32 v35, v35, v207, v147
	v_cvt_pk_bf16_f32 v234, v32, v33
	v_cvt_pk_bf16_f32 v235, v34, v35
	s_nop 0
	global_store_dwordx2 v243, v[234:235], s[12:13] offset:1024
	v_mul_f32_e32 v36, v36, v232
	v_mul_f32_e32 v37, v37, v232
	v_mul_f32_e32 v38, v38, v232
	v_mul_f32_e32 v39, v39, v232
	v_mul_f32_e32 v36, v132, v36
	v_mul_f32_e32 v37, v133, v37
	v_mul_f32_e32 v38, v134, v38
	v_mul_f32_e32 v39, v135, v39
	v_fma_f32 v36, v36, v208, v148
	v_fma_f32 v37, v37, v209, v149
	v_fma_f32 v38, v38, v210, v150
	v_fma_f32 v39, v39, v211, v151
	v_cvt_pk_bf16_f32 v234, v36, v37
	v_cvt_pk_bf16_f32 v235, v38, v39
	s_nop 0
	global_store_dwordx2 v248, v[234:235], s[12:13] offset:1024
	v_mul_f32_e32 v40, v40, v232
	v_mul_f32_e32 v41, v41, v232
	v_mul_f32_e32 v42, v42, v232
	v_mul_f32_e32 v43, v43, v232
	v_mul_f32_e32 v40, v136, v40
	v_mul_f32_e32 v41, v137, v41
	v_mul_f32_e32 v42, v138, v42
	v_mul_f32_e32 v43, v139, v43
	v_fma_f32 v40, v40, v212, v152
	v_fma_f32 v41, v41, v213, v153
	v_fma_f32 v42, v42, v214, v154
	v_fma_f32 v43, v43, v215, v155
	v_cvt_pk_bf16_f32 v234, v40, v41
	v_cvt_pk_bf16_f32 v235, v42, v43
	s_nop 0
	global_store_dwordx2 v249, v[234:235], s[12:13] offset:1024
	v_mul_f32_e32 v44, v44, v232
	v_mul_f32_e32 v45, v45, v232
	v_mul_f32_e32 v46, v46, v232
	v_mul_f32_e32 v47, v47, v232
	v_mul_f32_e32 v44, v140, v44
	v_mul_f32_e32 v45, v141, v45
	v_mul_f32_e32 v46, v142, v46
	v_mul_f32_e32 v47, v143, v47
	v_fma_f32 v44, v44, v216, v156
	v_fma_f32 v45, v45, v217, v157
	v_fma_f32 v46, v46, v218, v158
	v_fma_f32 v47, v47, v219, v159
	v_cvt_pk_bf16_f32 v234, v44, v45
	v_cvt_pk_bf16_f32 v235, v46, v47
	s_nop 0
	global_store_dwordx2 v250, v[234:235], s[12:13] offset:1024
	v_mul_f32_e32 v48, v48, v233
	v_mul_f32_e32 v49, v49, v233
	v_mul_f32_e32 v50, v50, v233
	v_mul_f32_e32 v51, v51, v233
	v_mul_f32_e32 v48, v128, v48
	v_mul_f32_e32 v49, v129, v49
	v_mul_f32_e32 v50, v130, v50
	v_mul_f32_e32 v51, v131, v51
	v_fma_f32 v48, v48, v204, v144
	v_fma_f32 v49, v49, v205, v145
	v_fma_f32 v50, v50, v206, v146
	v_fma_f32 v51, v51, v207, v147
	v_cvt_pk_bf16_f32 v234, v48, v49
	v_cvt_pk_bf16_f32 v235, v50, v51
	s_nop 0
	global_store_dwordx2 v244, v[234:235], s[12:13] offset:1024
	v_mul_f32_e32 v52, v52, v233
	v_mul_f32_e32 v53, v53, v233
	v_mul_f32_e32 v54, v54, v233
	v_mul_f32_e32 v55, v55, v233
	v_mul_f32_e32 v52, v132, v52
	v_mul_f32_e32 v53, v133, v53
	v_mul_f32_e32 v54, v134, v54
	v_mul_f32_e32 v55, v135, v55
	v_fma_f32 v52, v52, v208, v148
	v_fma_f32 v53, v53, v209, v149
	v_fma_f32 v54, v54, v210, v150
	v_fma_f32 v55, v55, v211, v151
	v_cvt_pk_bf16_f32 v234, v52, v53
	v_cvt_pk_bf16_f32 v235, v54, v55
	s_nop 0
	global_store_dwordx2 v251, v[234:235], s[12:13] offset:1024
	v_mul_f32_e32 v56, v56, v233
	v_mul_f32_e32 v57, v57, v233
	v_mul_f32_e32 v58, v58, v233
	v_mul_f32_e32 v59, v59, v233
	v_mul_f32_e32 v56, v136, v56
	v_mul_f32_e32 v57, v137, v57
	v_mul_f32_e32 v58, v138, v58
	v_mul_f32_e32 v59, v139, v59
	v_fma_f32 v56, v56, v212, v152
	v_fma_f32 v57, v57, v213, v153
	v_fma_f32 v58, v58, v214, v154
	v_fma_f32 v59, v59, v215, v155
	v_cvt_pk_bf16_f32 v234, v56, v57
	v_cvt_pk_bf16_f32 v235, v58, v59
	s_nop 0
	global_store_dwordx2 v246, v[234:235], s[12:13] offset:1024
	v_mul_f32_e32 v60, v60, v233
	v_mul_f32_e32 v61, v61, v233
	v_mul_f32_e32 v62, v62, v233
	v_mul_f32_e32 v63, v63, v233
	v_mul_f32_e32 v60, v140, v60
	v_mul_f32_e32 v61, v141, v61
	v_mul_f32_e32 v62, v142, v62
	v_mul_f32_e32 v63, v143, v63
	v_fma_f32 v60, v60, v216, v156
	v_fma_f32 v61, v61, v217, v157
	v_fma_f32 v62, v62, v218, v158
	v_fma_f32 v63, v63, v219, v159
	v_cvt_pk_bf16_f32 v234, v60, v61
	v_cvt_pk_bf16_f32 v235, v62, v63
	s_nop 0
	global_store_dwordx2 v247, v[234:235], s[12:13] offset:1024
	s_waitcnt vmcnt(24)
; DI unsigned pk2(float lo, float hi) { unsigned r; asm volatile("v_cvt_pk_bf16_f32 %0, %1, %2" : "=v"(r) : "v"(lo), "v"(hi)); return r; }
; DI float shx(float v, int m, int lane) { return __int_as_float(__builtin_amdgcn_ds_bpermute((lane ^ m) << 2, __float_as_int(v))); }
; DI void norm_rows(const Params& p, int layer, int row0, int nrows, int wstart, int wstride, int tid) {
;     ...
;     for (int i = 0; i < 4; ++i) { sa += va[i].x * va[i].x + va[i].y * va[i].y + va[i].z * va[i].z + va[i].w * va[i].w; sb += vb[i].x * vb[i].x + vb[i].y * vb[i].y + vb[i].z * vb[i].z + vb[i].w * vb[i].w; }
; #pragma unroll
;     for (int o = 32; o >= 1; o >>= 1) { sa += shx(sa, o, lane); sb += shx(sb, o, lane); }
; #pragma unroll
;     for (int rr = 0; rr < 2; ++rr) {
;       const int row = rr ? rowb : rowa; const float rinv = rsqrtf((rr ? sb : sa) * (1.0f / 1024.0f) + EPS);
;       if (layer < NLAYER) {
;         const int b = row >> 13; const float* md = modb + (size_t)(layer * 4 + b) * 3072; const float* g = p.norm_g + layer * 1024;
; #pragma unroll
;         for (int i = 0; i < 4; ++i) {
;           const float4 x4 = rr ? vb[i] : va[i];
;           const int e = i * 256 + lane * 4;
;           const float4 g4 = *(const float4*)(g + e), sh = *(const float4*)(md + e), sc = *(const float4*)(md + 1024 + e);
;           uint2 w;
;           w.x = pk2(x4.x * rinv * g4.x * (1.f + sc.x) + sh.x, x4.y * rinv * g4.y * (1.f + sc.y) + sh.y);
;           w.y = pk2(x4.z * rinv * g4.z * (1.f + sc.z) + sh.z, x4.w * rinv * g4.w * (1.f + sc.w) + sh.w);
;           *(uint2*)(h + wimg_off(row, e, DM)) = w;
	v_mul_f32_e32 v220, v65, v65
	v_mul_f32_e32 v224, v81, v81
	v_fmac_f32_e32 v220, v64, v64
	v_fmac_f32_e32 v224, v80, v80
	v_fmac_f32_e32 v220, v66, v66
	v_fmac_f32_e32 v224, v82, v82
	v_fmac_f32_e32 v220, v67, v67
	v_fmac_f32_e32 v224, v83, v83
	v_mul_f32_e32 v221, v69, v69
	v_mul_f32_e32 v225, v85, v85
	v_fmac_f32_e32 v221, v68, v68
	v_fmac_f32_e32 v225, v84, v84
	v_fmac_f32_e32 v221, v70, v70
	v_fmac_f32_e32 v225, v86, v86
	v_fmac_f32_e32 v221, v71, v71
	v_fmac_f32_e32 v225, v87, v87
	v_mul_f32_e32 v222, v73, v73
	v_mul_f32_e32 v226, v89, v89
	v_fmac_f32_e32 v222, v72, v72
	v_fmac_f32_e32 v226, v88, v88
	v_fmac_f32_e32 v222, v74, v74
	v_fmac_f32_e32 v226, v90, v90
	v_fmac_f32_e32 v222, v75, v75
	v_fmac_f32_e32 v226, v91, v91
	v_mul_f32_e32 v223, v77, v77
	v_mul_f32_e32 v227, v93, v93
	v_fmac_f32_e32 v223, v76, v76
	v_fmac_f32_e32 v227, v92, v92
	v_fmac_f32_e32 v223, v78, v78
	v_fmac_f32_e32 v227, v94, v94
	v_fmac_f32_e32 v223, v79, v79
	v_fmac_f32_e32 v227, v95, v95
	v_add_f32_e32 v228, v220, v221
	v_add_f32_e32 v229, v224, v225
	v_add_f32_e32 v228, v228, v222
	v_add_f32_e32 v229, v229, v226
	v_add_f32_e32 v228, v228, v223
	v_add_f32_e32 v229, v229, v227
	ds_bpermute_b32 v230, v236, v228
	ds_bpermute_b32 v231, v236, v229
	s_waitcnt lgkmcnt(0)
	v_add_f32_e32 v228, v228, v230
	v_add_f32_e32 v229, v229, v231
	ds_bpermute_b32 v230, v237, v228
	ds_bpermute_b32 v231, v237, v229
	s_waitcnt lgkmcnt(0)
	v_add_f32_e32 v228, v228, v230
	v_add_f32_e32 v229, v229, v231
	ds_bpermute_b32 v230, v238, v228
	ds_bpermute_b32 v231, v238, v229
	s_waitcnt lgkmcnt(0)
	v_add_f32_e32 v228, v228, v230
	v_add_f32_e32 v229, v229, v231
	ds_bpermute_b32 v230, v239, v228
	ds_bpermute_b32 v231, v239, v229
	s_waitcnt lgkmcnt(0)
	v_add_f32_e32 v228, v228, v230
	v_add_f32_e32 v229, v229, v231
	ds_bpermute_b32 v230, v240, v228
	ds_bpermute_b32 v231, v240, v229
	s_waitcnt lgkmcnt(0)
	v_add_f32_e32 v228, v228, v230
	v_add_f32_e32 v229, v229, v231
	ds_bpermute_b32 v230, v241, v228
	ds_bpermute_b32 v231, v241, v229
	s_waitcnt lgkmcnt(0)
	v_add_f32_e32 v228, v228, v230
	v_add_f32_e32 v229, v229, v231
	v_fma_f32 v228, v228, s14, v162
	v_fma_f32 v229, v229, s14, v162
	v_rsq_f32_e32 v232, v228
	v_rsq_f32_e32 v233, v229
	s_nop 0
	v_mul_f32_e32 v64, v64, v232
	v_mul_f32_e32 v65, v65, v232
	v_mul_f32_e32 v66, v66, v232
	v_mul_f32_e32 v67, v67, v232
	v_mul_f32_e32 v64, v128, v64
	v_mul_f32_e32 v65, v129, v65
	v_mul_f32_e32 v66, v130, v66
	v_mul_f32_e32 v67, v131, v67
	v_fma_f32 v64, v64, v204, v144
	v_fma_f32 v65, v65, v205, v145
	v_fma_f32 v66, v66, v206, v146
	v_fma_f32 v67, v67, v207, v147
	v_cvt_pk_bf16_f32 v234, v64, v65
	v_cvt_pk_bf16_f32 v235, v66, v67
	s_nop 0
	global_store_dwordx2 v243, v[234:235], s[12:13] offset:2048
	v_mul_f32_e32 v68, v68, v232
	v_mul_f32_e32 v69, v69, v232
	v_mul_f32_e32 v70, v70, v232
	v_mul_f32_e32 v71, v71, v232
	v_mul_f32_e32 v68, v132, v68
	v_mul_f32_e32 v69, v133, v69
	v_mul_f32_e32 v70, v134, v70
	v_mul_f32_e32 v71, v135, v71
	v_fma_f32 v68, v68, v208, v148
	v_fma_f32 v69, v69, v209, v149
	v_fma_f32 v70, v70, v210, v150
	v_fma_f32 v71, v71, v211, v151
	v_cvt_pk_bf16_f32 v234, v68, v69
	v_cvt_pk_bf16_f32 v235, v70, v71
	s_nop 0
	global_store_dwordx2 v248, v[234:235], s[12:13] offset:2048
	v_mul_f32_e32 v72, v72, v232
	v_mul_f32_e32 v73, v73, v232
	v_mul_f32_e32 v74, v74, v232
	v_mul_f32_e32 v75, v75, v232
	v_mul_f32_e32 v72, v136, v72
	v_mul_f32_e32 v73, v137, v73
	v_mul_f32_e32 v74, v138, v74
	v_mul_f32_e32 v75, v139, v75
	v_fma_f32 v72, v72, v212, v152
	v_fma_f32 v73, v73, v213, v153
	v_fma_f32 v74, v74, v214, v154
	v_fma_f32 v75, v75, v215, v155
	v_cvt_pk_bf16_f32 v234, v72, v73
	v_cvt_pk_bf16_f32 v235, v74, v75
	s_nop 0
	global_store_dwordx2 v249, v[234:235], s[12:13] offset:2048
	v_mul_f32_e32 v76, v76, v232
	v_mul_f32_e32 v77, v77, v232
	v_mul_f32_e32 v78, v78, v232
	v_mul_f32_e32 v79, v79, v232
	v_mul_f32_e32 v76, v140, v76
	v_mul_f32_e32 v77, v141, v77
	v_mul_f32_e32 v78, v142, v78
	v_mul_f32_e32 v79, v143, v79
	v_fma_f32 v76, v76, v216, v156
	v_fma_f32 v77, v77, v217, v157
	v_fma_f32 v78, v78, v218, v158
	v_fma_f32 v79, v79, v219, v159
	v_cvt_pk_bf16_f32 v234, v76, v77
	v_cvt_pk_bf16_f32 v235, v78, v79
	s_nop 0
	global_store_dwordx2 v250, v[234:235], s[12:13] offset:2048
	v_mul_f32_e32 v80, v80, v233
	v_mul_f32_e32 v81, v81, v233
	v_mul_f32_e32 v82, v82, v233
	v_mul_f32_e32 v83, v83, v233
	v_mul_f32_e32 v80, v128, v80
	v_mul_f32_e32 v81, v129, v81
	v_mul_f32_e32 v82, v130, v82
	v_mul_f32_e32 v83, v131, v83
	v_fma_f32 v80, v80, v204, v144
	v_fma_f32 v81, v81, v205, v145
	v_fma_f32 v82, v82, v206, v146
	v_fma_f32 v83, v83, v207, v147
	v_cvt_pk_bf16_f32 v234, v80, v81
	v_cvt_pk_bf16_f32 v235, v82, v83
	s_nop 0
	global_store_dwordx2 v244, v[234:235], s[12:13] offset:2048
	v_mul_f32_e32 v84, v84, v233
	v_mul_f32_e32 v85, v85, v233
	v_mul_f32_e32 v86, v86, v233
	v_mul_f32_e32 v87, v87, v233
	v_mul_f32_e32 v84, v132, v84
	v_mul_f32_e32 v85, v133, v85
	v_mul_f32_e32 v86, v134, v86
	v_mul_f32_e32 v87, v135, v87
	v_fma_f32 v84, v84, v208, v148
	v_fma_f32 v85, v85, v209, v149
	v_fma_f32 v86, v86, v210, v150
	v_fma_f32 v87, v87, v211, v151
	v_cvt_pk_bf16_f32 v234, v84, v85
	v_cvt_pk_bf16_f32 v235, v86, v87
	s_nop 0
	global_store_dwordx2 v251, v[234:235], s[12:13] offset:2048
	v_mul_f32_e32 v88, v88, v233
	v_mul_f32_e32 v89, v89, v233
	v_mul_f32_e32 v90, v90, v233
	v_mul_f32_e32 v91, v91, v233
	v_mul_f32_e32 v88, v136, v88
	v_mul_f32_e32 v89, v137, v89
	v_mul_f32_e32 v90, v138, v90
	v_mul_f32_e32 v91, v139, v91
	v_fma_f32 v88, v88, v212, v152
	v_fma_f32 v89, v89, v213, v153
	v_fma_f32 v90, v90, v214, v154
	v_fma_f32 v91, v91, v215, v155
	v_cvt_pk_bf16_f32 v234, v88, v89
	v_cvt_pk_bf16_f32 v235, v90, v91
	s_nop 0
	global_store_dwordx2 v246, v[234:235], s[12:13] offset:2048
	v_mul_f32_e32 v92, v92, v233
	v_mul_f32_e32 v93, v93, v233
	v_mul_f32_e32 v94, v94, v233
	v_mul_f32_e32 v95, v95, v233
	v_mul_f32_e32 v92, v140, v92
	v_mul_f32_e32 v93, v141, v93
	v_mul_f32_e32 v94, v142, v94
	v_mul_f32_e32 v95, v143, v95
	v_fma_f32 v92, v92, v216, v156
	v_fma_f32 v93, v93, v217, v157
	v_fma_f32 v94, v94, v218, v158
	v_fma_f32 v95, v95, v219, v159
	v_cvt_pk_bf16_f32 v234, v92, v93
	v_cvt_pk_bf16_f32 v235, v94, v95
	s_nop 0
	global_store_dwordx2 v247, v[234:235], s[12:13] offset:2048
	s_waitcnt vmcnt(24)
; DI unsigned pk2(float lo, float hi) { unsigned r; asm volatile("v_cvt_pk_bf16_f32 %0, %1, %2" : "=v"(r) : "v"(lo), "v"(hi)); return r; }
; DI float shx(float v, int m, int lane) { return __int_as_float(__builtin_amdgcn_ds_bpermute((lane ^ m) << 2, __float_as_int(v))); }
; DI void norm_rows(const Params& p, int layer, int row0, int nrows, int wstart, int wstride, int tid) {
;     ...
;     for (int i = 0; i < 4; ++i) { sa += va[i].x * va[i].x + va[i].y * va[i].y + va[i].z * va[i].z + va[i].w * va[i].w; sb += vb[i].x * vb[i].x + vb[i].y * vb[i].y + vb[i].z * vb[i].z + vb[i].w * vb[i].w; }
; #pragma unroll
;     for (int o = 32; o >= 1; o >>= 1) { sa += shx(sa, o, lane); sb += shx(sb, o, lane); }
; #pragma unroll
;     for (int rr = 0; rr < 2; ++rr) {
;       const int row = rr ? rowb : rowa; const float rinv = rsqrtf((rr ? sb : sa) * (1.0f / 1024.0f) + EPS);
;       if (layer < NLAYER) {
;         const int b = row >> 13; const float* md = modb + (size_t)(layer * 4 + b) * 3072; const float* g = p.norm_g + layer * 1024;
; #pragma unroll
;         for (int i = 0; i < 4; ++i) {
;           const float4 x4 = rr ? vb[i] : va[i];
;           const int e = i * 256 + lane * 4;
;           const float4 g4 = *(const float4*)(g + e), sh = *(const float4*)(md + e), sc = *(const float4*)(md + 1024 + e);
;           uint2 w;
;           w.x = pk2(x4.x * rinv * g4.x * (1.f + sc.x) + sh.x, x4.y * rinv * g4.y * (1.f + sc.y) + sh.y);
;           w.y = pk2(x4.z * rinv * g4.z * (1.f + sc.z) + sh.z, x4.w * rinv * g4.w * (1.f + sc.w) + sh.w);
;           *(uint2*)(h + wimg_off(row, e, DM)) = w;
	v_mul_f32_e32 v220, v97, v97
	v_mul_f32_e32 v224, v113, v113
	v_fmac_f32_e32 v220, v96, v96
	v_fmac_f32_e32 v224, v112, v112
	v_fmac_f32_e32 v220, v98, v98
	v_fmac_f32_e32 v224, v114, v114
	v_fmac_f32_e32 v220, v99, v99
	v_fmac_f32_e32 v224, v115, v115
	v_mul_f32_e32 v221, v101, v101
	v_mul_f32_e32 v225, v117, v117
	v_fmac_f32_e32 v221, v100, v100
	v_fmac_f32_e32 v225, v116, v116
	v_fmac_f32_e32 v221, v102, v102
	v_fmac_f32_e32 v225, v118, v118
	v_fmac_f32_e32 v221, v103, v103
	v_fmac_f32_e32 v225, v119, v119
	v_mul_f32_e32 v222, v105, v105
	v_mul_f32_e32 v226, v121, v121
	v_fmac_f32_e32 v222, v104, v104
	v_fmac_f32_e32 v226, v120, v120
	v_fmac_f32_e32 v222, v106, v106
	v_fmac_f32_e32 v226, v122, v122
	v_fmac_f32_e32 v222, v107, v107
	v_fmac_f32_e32 v226, v123, v123
	v_mul_f32_e32 v223, v109, v109
	v_mul_f32_e32 v227, v125, v125
	v_fmac_f32_e32 v223, v108, v108
	v_fmac_f32_e32 v227, v124, v124
	v_fmac_f32_e32 v223, v110, v110
	v_fmac_f32_e32 v227, v126, v126
	v_fmac_f32_e32 v223, v111, v111
	v_fmac_f32_e32 v227, v127, v127
	v_add_f32_e32 v228, v220, v221
	v_add_f32_e32 v229, v224, v225
	v_add_f32_e32 v228, v228, v222
	v_add_f32_e32 v229, v229, v226
	v_add_f32_e32 v228, v228, v223
	v_add_f32_e32 v229, v229, v227
	ds_bpermute_b32 v230, v236, v228
	ds_bpermute_b32 v231, v236, v229
	s_waitcnt lgkmcnt(0)
	v_add_f32_e32 v228, v228, v230
	v_add_f32_e32 v229, v229, v231
	ds_bpermute_b32 v230, v237, v228
	ds_bpermute_b32 v231, v237, v229
	s_waitcnt lgkmcnt(0)
	v_add_f32_e32 v228, v228, v230
	v_add_f32_e32 v229, v229, v231
	ds_bpermute_b32 v230, v238, v228
	ds_bpermute_b32 v231, v238, v229
	s_waitcnt lgkmcnt(0)
	v_add_f32_e32 v228, v228, v230
	v_add_f32_e32 v229, v229, v231
	ds_bpermute_b32 v230, v239, v228
	ds_bpermute_b32 v231, v239, v229
	s_waitcnt lgkmcnt(0)
	v_add_f32_e32 v228, v228, v230
	v_add_f32_e32 v229, v229, v231
	ds_bpermute_b32 v230, v240, v228
	ds_bpermute_b32 v231, v240, v229
	s_waitcnt lgkmcnt(0)
	v_add_f32_e32 v228, v228, v230
	v_add_f32_e32 v229, v229, v231
	ds_bpermute_b32 v230, v241, v228
	ds_bpermute_b32 v231, v241, v229
	s_waitcnt lgkmcnt(0)
	v_add_f32_e32 v228, v228, v230
	v_add_f32_e32 v229, v229, v231
	v_fma_f32 v228, v228, s14, v162
	v_fma_f32 v229, v229, s14, v162
	v_rsq_f32_e32 v232, v228
	v_rsq_f32_e32 v233, v229
	s_nop 0
	v_mul_f32_e32 v96, v96, v232
	v_mul_f32_e32 v97, v97, v232
	v_mul_f32_e32 v98, v98, v232
	v_mul_f32_e32 v99, v99, v232
	v_mul_f32_e32 v96, v128, v96
	v_mul_f32_e32 v97, v129, v97
	v_mul_f32_e32 v98, v130, v98
	v_mul_f32_e32 v99, v131, v99
	v_fma_f32 v96, v96, v204, v144
	v_fma_f32 v97, v97, v205, v145
	v_fma_f32 v98, v98, v206, v146
	v_fma_f32 v99, v99, v207, v147
	v_cvt_pk_bf16_f32 v234, v96, v97
	v_cvt_pk_bf16_f32 v235, v98, v99
	s_nop 0
	global_store_dwordx2 v243, v[234:235], s[12:13] offset:3072
	v_mul_f32_e32 v100, v100, v232
	v_mul_f32_e32 v101, v101, v232
	v_mul_f32_e32 v102, v102, v232
	v_mul_f32_e32 v103, v103, v232
	v_mul_f32_e32 v100, v132, v100
	v_mul_f32_e32 v101, v133, v101
	v_mul_f32_e32 v102, v134, v102
	v_mul_f32_e32 v103, v135, v103
	v_fma_f32 v100, v100, v208, v148
	v_fma_f32 v101, v101, v209, v149
	v_fma_f32 v102, v102, v210, v150
	v_fma_f32 v103, v103, v211, v151
	v_cvt_pk_bf16_f32 v234, v100, v101
	v_cvt_pk_bf16_f32 v235, v102, v103
	s_nop 0
	global_store_dwordx2 v248, v[234:235], s[12:13] offset:3072
	v_mul_f32_e32 v104, v104, v232
	v_mul_f32_e32 v105, v105, v232
	v_mul_f32_e32 v106, v106, v232
	v_mul_f32_e32 v107, v107, v232
	v_mul_f32_e32 v104, v136, v104
	v_mul_f32_e32 v105, v137, v105
	v_mul_f32_e32 v106, v138, v106
	v_mul_f32_e32 v107, v139, v107
	v_fma_f32 v104, v104, v212, v152
	v_fma_f32 v105, v105, v213, v153
	v_fma_f32 v106, v106, v214, v154
	v_fma_f32 v107, v107, v215, v155
	v_cvt_pk_bf16_f32 v234, v104, v105
	v_cvt_pk_bf16_f32 v235, v106, v107
	s_nop 0
	global_store_dwordx2 v249, v[234:235], s[12:13] offset:3072
	v_mul_f32_e32 v108, v108, v232
	v_mul_f32_e32 v109, v109, v232
	v_mul_f32_e32 v110, v110, v232
	v_mul_f32_e32 v111, v111, v232
	v_mul_f32_e32 v108, v140, v108
	v_mul_f32_e32 v109, v141, v109
	v_mul_f32_e32 v110, v142, v110
	v_mul_f32_e32 v111, v143, v111
	v_fma_f32 v108, v108, v216, v156
	v_fma_f32 v109, v109, v217, v157
	v_fma_f32 v110, v110, v218, v158
	v_fma_f32 v111, v111, v219, v159
	v_cvt_pk_bf16_f32 v234, v108, v109
	v_cvt_pk_bf16_f32 v235, v110, v111
	s_nop 0
	global_store_dwordx2 v250, v[234:235], s[12:13] offset:3072
	v_mul_f32_e32 v112, v112, v233
	v_mul_f32_e32 v113, v113, v233
	v_mul_f32_e32 v114, v114, v233
	v_mul_f32_e32 v115, v115, v233
	v_mul_f32_e32 v112, v128, v112
	v_mul_f32_e32 v113, v129, v113
	v_mul_f32_e32 v114, v130, v114
	v_mul_f32_e32 v115, v131, v115
	v_fma_f32 v112, v112, v204, v144
	v_fma_f32 v113, v113, v205, v145
	v_fma_f32 v114, v114, v206, v146
	v_fma_f32 v115, v115, v207, v147
	v_cvt_pk_bf16_f32 v234, v112, v113
	v_cvt_pk_bf16_f32 v235, v114, v115
	s_nop 0
	global_store_dwordx2 v244, v[234:235], s[12:13] offset:3072
	v_mul_f32_e32 v116, v116, v233
	v_mul_f32_e32 v117, v117, v233
	v_mul_f32_e32 v118, v118, v233
	v_mul_f32_e32 v119, v119, v233
	v_mul_f32_e32 v116, v132, v116
	v_mul_f32_e32 v117, v133, v117
	v_mul_f32_e32 v118, v134, v118
	v_mul_f32_e32 v119, v135, v119
	v_fma_f32 v116, v116, v208, v148
	v_fma_f32 v117, v117, v209, v149
	v_fma_f32 v118, v118, v210, v150
	v_fma_f32 v119, v119, v211, v151
	v_cvt_pk_bf16_f32 v234, v116, v117
	v_cvt_pk_bf16_f32 v235, v118, v119
	s_nop 0
	global_store_dwordx2 v251, v[234:235], s[12:13] offset:3072
	v_mul_f32_e32 v120, v120, v233
	v_mul_f32_e32 v121, v121, v233
	v_mul_f32_e32 v122, v122, v233
	v_mul_f32_e32 v123, v123, v233
	v_mul_f32_e32 v120, v136, v120
	v_mul_f32_e32 v121, v137, v121
	v_mul_f32_e32 v122, v138, v122
	v_mul_f32_e32 v123, v139, v123
	v_fma_f32 v120, v120, v212, v152
	v_fma_f32 v121, v121, v213, v153
	v_fma_f32 v122, v122, v214, v154
	v_fma_f32 v123, v123, v215, v155
	v_cvt_pk_bf16_f32 v234, v120, v121
	v_cvt_pk_bf16_f32 v235, v122, v123
	s_nop 0
	global_store_dwordx2 v246, v[234:235], s[12:13] offset:3072
	v_mul_f32_e32 v124, v124, v233
	v_mul_f32_e32 v125, v125, v233
	v_mul_f32_e32 v126, v126, v233
	v_mul_f32_e32 v127, v127, v233
	v_mul_f32_e32 v124, v140, v124
	v_mul_f32_e32 v125, v141, v125
	v_mul_f32_e32 v126, v142, v126
	v_mul_f32_e32 v127, v143, v127
	v_fma_f32 v124, v124, v216, v156
	v_fma_f32 v125, v125, v217, v157
	v_fma_f32 v126, v126, v218, v158
	v_fma_f32 v127, v127, v219, v159
	v_cvt_pk_bf16_f32 v234, v124, v125
	v_cvt_pk_bf16_f32 v235, v126, v127
	s_nop 0
	global_store_dwordx2 v247, v[234:235], s[12:13] offset:3072
	s_branch .LBB0_410
; DI void norm_rows(const Params& p, int layer, int row0, int nrows, int wstart, int wstride, int tid) {
;   unsigned char* wsb = ows(p);
;   const float* xin = (layer == 0) ? p.x : p.out;
;   const int wid = tid >> 6, lane = tid & 63;
;   bf16_t* h = (bf16_t*)(wsb + WS_H);
;   const float* modb = (const float*)(wsb + WS_MOD);
;   for (int rowa = row0 + wstart + wid; rowa < row0 + nrows; rowa += 2 * wstride) {
;     const int rowb = (rowa + wstride < row0 + nrows) ? rowa + wstride : rowa;
;     float4 va[4], vb[4]; float sa = 0.f, sb = 0.f;
; #pragma unroll
;     for (int i = 0; i < 4; ++i) { va[i] = *(const float4*)(xin + (size_t)rowa * DM + i * 256 + lane * 4); vb[i] = *(const float4*)(xin + (size_t)rowb * DM + i * 256 + lane * 4); }
; DI void norm_unit(const Params& p, int layer, int half, int nu, int tid) { norm_rows(p, layer, half * HROWS + nu * 64, 64, 0, 8, tid); }
.Lp4n_orig:
	s_lshl_b32 s4, s23, 6
	s_add_i32 s2, s4, 0xffff9040
	s_addk_i32 s4, 0x9000
	v_add_u32_e32 v32, s4, v1
	v_and_b32_e32 v1, 63, v0
	v_lshlrev_b32_e32 v34, 2, v1
	v_lshlrev_b32_e32 v160, 4, v1
	v_lshlrev_b32_e32 v1, 3, v0
	v_or_b32_e32 v38, 0x100, v34
	v_lshlrev_b32_e32 v0, 9, v0
	v_or_b32_e32 v40, 0x200, v34
	v_and_b32_e32 v44, 0x7000, v0
	v_lshlrev_b32_e32 v0, 7, v38
	v_or_b32_e32 v42, 0x300, v34
	v_and_b32_e32 v46, 0xf000, v0
	v_lshlrev_b32_e32 v0, 7, v40
	v_readlane_b32 s4, v254, 39
	v_and_b32_e32 v48, 0x17000, v0
	v_lshlrev_b32_e32 v0, 7, v42
	v_readlane_b32 s5, v254, 40
	v_ashrrev_i32_e32 v33, 31, v32
	v_and_b32_e32 v35, 56, v1
	v_and_b32_e32 v50, 0x1f000, v0
	v_lshl_add_u64 v[52:53], s[4:5], 0, v[160:161]
	v_readlane_b32 s4, v252, 24
	v_lshlrev_b64 v[0:1], 12, v[32:33]
	v_readlane_b32 s5, v252, 25
	v_readlane_b32 s18, v252, 38
	v_readlane_b32 s19, v252, 39
	v_or_b32_e32 v0, v0, v160
	v_lshl_add_u64 v[36:37], s[36:37], 0, v[160:161]
	v_xor_b32_e32 v39, 0x80, v34
	v_xor_b32_e32 v41, 64, v34
	v_xor_b32_e32 v43, 32, v34
	v_xor_b32_e32 v45, 16, v34
	v_xor_b32_e32 v47, 8, v34
	v_xor_b32_e32 v49, 4, v34
	v_lshl_add_u64 v[54:55], s[18:19], 0, v[160:161]
	v_lshlrev_b32_e32 v51, 6, v32
	v_lshl_add_u64 v[56:57], s[36:37], 0, v[0:1]
	s_mov_b64 s[4:5], 0
	v_readlane_b32 s6, v252, 26
	v_readlane_b32 s7, v252, 27
	v_readlane_b32 s8, v252, 28
	v_readlane_b32 s9, v252, 29
	v_readlane_b32 s10, v252, 30
	v_readlane_b32 s11, v252, 31
	v_readlane_b32 s12, v252, 32
	v_readlane_b32 s13, v252, 33
	v_readlane_b32 s14, v252, 34
	v_readlane_b32 s15, v252, 35
	v_readlane_b32 s16, v252, 36
	v_readlane_b32 s17, v252, 37
	s_branch .LBB0_626
